# v35 + GEMM K-loop LDS-DMA addresses in SGPR-base form (16 v_lshl_add_u64 per two K-tiles removed in all 8 loops; +0x80 bases by SALU)
# baseline (speedup 1.0000x reference)
.LBB0_90:
	ds_read_b128 v[130:133], v179
	ds_read_b128 v[134:137], v179 offset:1024
	ds_read_b128 v[138:141], v179 offset:2048
	ds_read_b128 v[142:145], v179 offset:3072
	ds_read_b128 v[166:169], v180
	ds_read_b128 v[170:173], v180 offset:1024
	ds_read_b128 v[184:187], v180 offset:2048
	ds_read_b128 v[188:191], v180 offset:3072
	s_add_u32 s42, s40, 0xfff80080
	s_addc_u32 s43, s41, -1
	s_cmp_eq_u32 s77, 28
	s_cselect_b32 s45, s31, s43
	s_cselect_b32 s44, s39, s42
	s_cselect_b32 s43, s29, s76
	s_cselect_b32 s42, s74, s75
	s_add_i32 m0, s52, 0xc000
	ds_read_b128 v[192:195], v181
	ds_read_b128 v[196:199], v181 offset:1024
	ds_read_b128 v[200:203], v181 offset:2048
	ds_read_b128 v[204:207], v181 offset:3072
	ds_read_b128 v[208:211], v181 offset:4096
	ds_read_b128 v[212:215], v181 offset:5120
	ds_read_b128 v[216:219], v181 offset:6144
	ds_read_b128 v[220:223], v181 offset:7168
	global_load_lds_dwordx4 v158, s[40:41]
	s_add_i32 m0, s52, 0xe000
	s_nop 0
	global_load_lds_dwordx4 v160, s[40:41]
	s_waitcnt vmcnt(8)
	s_waitcnt lgkmcnt(0)
	s_barrier
	s_setprio 1
	s_waitcnt lgkmcnt(0)
	v_mfma_f32_16x16x32_bf16 v[126:129], v[130:133], v[192:195], v[126:129]
	v_mfma_f32_16x16x32_bf16 v[122:125], v[138:141], v[192:195], v[122:125]
	v_mfma_f32_16x16x32_bf16 v[118:121], v[130:133], v[200:203], v[118:121]
	v_mfma_f32_16x16x32_bf16 v[110:113], v[138:141], v[200:203], v[110:113]
	v_mfma_f32_16x16x32_bf16 v[102:105], v[130:133], v[208:211], v[102:105]
	v_mfma_f32_16x16x32_bf16 v[94:97], v[138:141], v[208:211], v[94:97]
	v_mfma_f32_16x16x32_bf16 v[86:89], v[130:133], v[216:219], v[86:89]
	v_mfma_f32_16x16x32_bf16 v[78:81], v[138:141], v[216:219], v[78:81]
	v_mfma_f32_16x16x32_bf16 v[126:129], v[134:137], v[196:199], v[126:129]
	v_mfma_f32_16x16x32_bf16 v[122:125], v[142:145], v[196:199], v[122:125]
	v_mfma_f32_16x16x32_bf16 v[118:121], v[134:137], v[204:207], v[118:121]
	v_mfma_f32_16x16x32_bf16 v[110:113], v[142:145], v[204:207], v[110:113]
	v_mfma_f32_16x16x32_bf16 v[102:105], v[134:137], v[212:215], v[102:105]
	v_mfma_f32_16x16x32_bf16 v[94:97], v[142:145], v[212:215], v[94:97]
	v_mfma_f32_16x16x32_bf16 v[86:89], v[134:137], v[220:223], v[86:89]
	v_mfma_f32_16x16x32_bf16 v[78:81], v[142:145], v[220:223], v[78:81]
	s_setprio 0
	s_setprio 1
	v_mfma_f32_16x16x32_bf16 v[114:117], v[166:169], v[192:195], v[114:117]
	v_mfma_f32_16x16x32_bf16 v[106:109], v[184:187], v[192:195], v[106:109]
	v_mfma_f32_16x16x32_bf16 v[98:101], v[166:169], v[200:203], v[98:101]
	v_mfma_f32_16x16x32_bf16 v[90:93], v[184:187], v[200:203], v[90:93]
	v_mfma_f32_16x16x32_bf16 v[82:85], v[166:169], v[208:211], v[82:85]
	v_mfma_f32_16x16x32_bf16 v[74:77], v[184:187], v[208:211], v[74:77]
	v_mfma_f32_16x16x32_bf16 v[70:73], v[166:169], v[216:219], v[70:73]
	v_mfma_f32_16x16x32_bf16 v[66:69], v[184:187], v[216:219], v[66:69]
	v_mfma_f32_16x16x32_bf16 v[114:117], v[170:173], v[196:199], v[114:117]
	v_mfma_f32_16x16x32_bf16 v[106:109], v[188:191], v[196:199], v[106:109]
	v_mfma_f32_16x16x32_bf16 v[98:101], v[170:173], v[204:207], v[98:101]
	v_mfma_f32_16x16x32_bf16 v[90:93], v[188:191], v[204:207], v[90:93]
	v_mfma_f32_16x16x32_bf16 v[82:85], v[170:173], v[212:215], v[82:85]
	v_mfma_f32_16x16x32_bf16 v[74:77], v[188:191], v[212:215], v[74:77]
	v_mfma_f32_16x16x32_bf16 v[70:73], v[170:173], v[220:223], v[70:73]
	v_mfma_f32_16x16x32_bf16 v[66:69], v[188:191], v[220:223], v[66:69]
	s_setprio 0
	s_barrier
	s_add_i32 s78, s63, s49
	s_mov_b32 m0, s78
	ds_read_b128 v[192:195], v181 offset:16384
	ds_read_b128 v[196:199], v181 offset:17408
	ds_read_b128 v[200:203], v181 offset:18432
	ds_read_b128 v[204:207], v181 offset:19456
	ds_read_b128 v[208:211], v181 offset:20480
	ds_read_b128 v[212:215], v181 offset:21504
	ds_read_b128 v[216:219], v181 offset:22528
	ds_read_b128 v[220:223], v181 offset:23552
	global_load_lds_dwordx4 v150, s[42:43]
	s_add_u32 s98, s42, 0x80
	s_addc_u32 s99, s43, 0
	s_add_i32 m0, s78, 0x2000
	s_add_u32 s78, s42, 0x80000
	s_addc_u32 s79, s43, 0
	s_add_i32 s80, s64, s49
	global_load_lds_dwordx4 v146, s[42:43]
	s_mov_b32 m0, s80
	s_nop 0
	global_load_lds_dwordx4 v150, s[78:79]
	s_add_i32 m0, s80, 0x2000
	s_nop 0
	global_load_lds_dwordx4 v146, s[78:79]
	s_mov_b32 m0, s52
	s_nop 0
	global_load_lds_dwordx4 v152, s[44:45]
	s_mov_b32 m0, s53
	s_nop 0
	global_load_lds_dwordx4 v148, s[44:45]
	s_waitcnt vmcnt(8)
	s_waitcnt lgkmcnt(0)
	s_barrier
	s_setprio 1
	s_waitcnt lgkmcnt(0)
	v_mfma_f32_16x16x32_bf16 v[62:65], v[130:133], v[192:195], v[62:65]
	v_mfma_f32_16x16x32_bf16 v[58:61], v[138:141], v[192:195], v[58:61]
	v_mfma_f32_16x16x32_bf16 v[54:57], v[130:133], v[200:203], v[54:57]
	v_mfma_f32_16x16x32_bf16 v[46:49], v[138:141], v[200:203], v[46:49]
	v_mfma_f32_16x16x32_bf16 v[38:41], v[130:133], v[208:211], v[38:41]
	v_mfma_f32_16x16x32_bf16 v[30:33], v[138:141], v[208:211], v[30:33]
	v_mfma_f32_16x16x32_bf16 v[22:25], v[130:133], v[216:219], v[22:25]
	v_mfma_f32_16x16x32_bf16 v[14:17], v[138:141], v[216:219], v[14:17]
	v_mfma_f32_16x16x32_bf16 v[62:65], v[134:137], v[196:199], v[62:65]
	v_mfma_f32_16x16x32_bf16 v[58:61], v[142:145], v[196:199], v[58:61]
	v_mfma_f32_16x16x32_bf16 v[54:57], v[134:137], v[204:207], v[54:57]
	v_mfma_f32_16x16x32_bf16 v[46:49], v[142:145], v[204:207], v[46:49]
	v_mfma_f32_16x16x32_bf16 v[38:41], v[134:137], v[212:215], v[38:41]
	v_mfma_f32_16x16x32_bf16 v[30:33], v[142:145], v[212:215], v[30:33]
	v_mfma_f32_16x16x32_bf16 v[22:25], v[134:137], v[220:223], v[22:25]
	v_mfma_f32_16x16x32_bf16 v[14:17], v[142:145], v[220:223], v[14:17]
	s_setprio 0
	s_setprio 1
	v_mfma_f32_16x16x32_bf16 v[50:53], v[166:169], v[192:195], v[50:53]
	v_mfma_f32_16x16x32_bf16 v[42:45], v[184:187], v[192:195], v[42:45]
	v_mfma_f32_16x16x32_bf16 v[34:37], v[166:169], v[200:203], v[34:37]
	v_mfma_f32_16x16x32_bf16 v[26:29], v[184:187], v[200:203], v[26:29]
	v_mfma_f32_16x16x32_bf16 v[18:21], v[166:169], v[208:211], v[18:21]
	v_mfma_f32_16x16x32_bf16 v[10:13], v[184:187], v[208:211], v[10:13]
	v_mfma_f32_16x16x32_bf16 v[6:9], v[166:169], v[216:219], v[6:9]
	v_mfma_f32_16x16x32_bf16 v[2:5], v[184:187], v[216:219], v[2:5]
	v_mfma_f32_16x16x32_bf16 v[50:53], v[170:173], v[196:199], v[50:53]
	v_mfma_f32_16x16x32_bf16 v[42:45], v[188:191], v[196:199], v[42:45]
	v_mfma_f32_16x16x32_bf16 v[34:37], v[170:173], v[204:207], v[34:37]
	v_mfma_f32_16x16x32_bf16 v[26:29], v[188:191], v[204:207], v[26:29]
	v_mfma_f32_16x16x32_bf16 v[18:21], v[170:173], v[212:215], v[18:21]
	v_mfma_f32_16x16x32_bf16 v[10:13], v[188:191], v[212:215], v[10:13]
	v_mfma_f32_16x16x32_bf16 v[6:9], v[170:173], v[220:223], v[6:9]
	v_mfma_f32_16x16x32_bf16 v[2:5], v[188:191], v[220:223], v[2:5]
	s_setprio 0
	s_barrier
	s_add_u32 s100, s44, 0x80
	s_addc_u32 s101, s45, 0
	s_add_i32 s78, 0, 0x18000
	s_add_i32 s79, 0, 0x1c000
	v_add_u32_e32 v142, s78, v174
	v_add_u32_e32 v154, s79, v174
	ds_read_b128 v[130:133], v142
	ds_read_b128 v[134:137], v142 offset:1024
	ds_read_b128 v[138:141], v142 offset:2048
	ds_read_b128 v[142:145], v142 offset:3072
	ds_read_b128 v[166:169], v154
	ds_read_b128 v[170:173], v154 offset:1024
	ds_read_b128 v[184:187], v154 offset:2048
	ds_read_b128 v[188:191], v154 offset:3072
	s_add_u32 s44, s44, 0x80000
	s_addc_u32 s45, s45, 0
	s_mov_b32 m0, s54
	ds_read_b128 v[192:195], v181 offset:32768
	ds_read_b128 v[196:199], v181 offset:33792
	ds_read_b128 v[200:203], v181 offset:34816
	ds_read_b128 v[204:207], v181 offset:35840
	ds_read_b128 v[208:211], v181 offset:36864
	ds_read_b128 v[212:215], v181 offset:37888
	ds_read_b128 v[216:219], v181 offset:38912
	ds_read_b128 v[220:223], v181 offset:39936
	global_load_lds_dwordx4 v152, s[44:45]
	s_mov_b32 m0, s55
	s_nop 0
	global_load_lds_dwordx4 v148, s[44:45]
	s_waitcnt vmcnt(8)
	s_waitcnt lgkmcnt(0)
	s_barrier
	s_setprio 1
	s_waitcnt lgkmcnt(0)
	v_mfma_f32_16x16x32_bf16 v[126:129], v[130:133], v[192:195], v[126:129]
	v_mfma_f32_16x16x32_bf16 v[122:125], v[138:141], v[192:195], v[122:125]
	v_mfma_f32_16x16x32_bf16 v[118:121], v[130:133], v[200:203], v[118:121]
	v_mfma_f32_16x16x32_bf16 v[110:113], v[138:141], v[200:203], v[110:113]
	v_mfma_f32_16x16x32_bf16 v[102:105], v[130:133], v[208:211], v[102:105]
	v_mfma_f32_16x16x32_bf16 v[94:97], v[138:141], v[208:211], v[94:97]
	v_mfma_f32_16x16x32_bf16 v[86:89], v[130:133], v[216:219], v[86:89]
	v_mfma_f32_16x16x32_bf16 v[78:81], v[138:141], v[216:219], v[78:81]
	v_mfma_f32_16x16x32_bf16 v[126:129], v[134:137], v[196:199], v[126:129]
	v_mfma_f32_16x16x32_bf16 v[122:125], v[142:145], v[196:199], v[122:125]
	v_mfma_f32_16x16x32_bf16 v[118:121], v[134:137], v[204:207], v[118:121]
	v_mfma_f32_16x16x32_bf16 v[110:113], v[142:145], v[204:207], v[110:113]
	v_mfma_f32_16x16x32_bf16 v[102:105], v[134:137], v[212:215], v[102:105]
	v_mfma_f32_16x16x32_bf16 v[94:97], v[142:145], v[212:215], v[94:97]
	v_mfma_f32_16x16x32_bf16 v[86:89], v[134:137], v[220:223], v[86:89]
	v_mfma_f32_16x16x32_bf16 v[78:81], v[142:145], v[220:223], v[78:81]
	s_setprio 0
	s_setprio 1
	v_mfma_f32_16x16x32_bf16 v[114:117], v[166:169], v[192:195], v[114:117]
	v_mfma_f32_16x16x32_bf16 v[106:109], v[184:187], v[192:195], v[106:109]
	v_mfma_f32_16x16x32_bf16 v[98:101], v[166:169], v[200:203], v[98:101]
	v_mfma_f32_16x16x32_bf16 v[90:93], v[184:187], v[200:203], v[90:93]
	v_mfma_f32_16x16x32_bf16 v[82:85], v[166:169], v[208:211], v[82:85]
	v_mfma_f32_16x16x32_bf16 v[74:77], v[184:187], v[208:211], v[74:77]
	v_mfma_f32_16x16x32_bf16 v[70:73], v[166:169], v[216:219], v[70:73]
	v_mfma_f32_16x16x32_bf16 v[66:69], v[184:187], v[216:219], v[66:69]
	v_mfma_f32_16x16x32_bf16 v[114:117], v[170:173], v[196:199], v[114:117]
	v_mfma_f32_16x16x32_bf16 v[106:109], v[188:191], v[196:199], v[106:109]
	v_mfma_f32_16x16x32_bf16 v[98:101], v[170:173], v[204:207], v[98:101]
	v_mfma_f32_16x16x32_bf16 v[90:93], v[188:191], v[204:207], v[90:93]
	v_mfma_f32_16x16x32_bf16 v[82:85], v[170:173], v[212:215], v[82:85]
	v_mfma_f32_16x16x32_bf16 v[74:77], v[188:191], v[212:215], v[74:77]
	v_mfma_f32_16x16x32_bf16 v[70:73], v[170:173], v[220:223], v[70:73]
	v_mfma_f32_16x16x32_bf16 v[66:69], v[188:191], v[220:223], v[66:69]
	s_setprio 0
	s_barrier
	s_add_i32 s44, s78, s49
	s_mov_b32 m0, s44
	ds_read_b128 v[192:195], v181 offset:49152
	ds_read_b128 v[196:199], v181 offset:50176
	ds_read_b128 v[200:203], v181 offset:51200
	ds_read_b128 v[204:207], v181 offset:52224
	ds_read_b128 v[208:211], v181 offset:53248
	ds_read_b128 v[212:215], v181 offset:54272
	ds_read_b128 v[216:219], v181 offset:55296
	ds_read_b128 v[220:223], v181 offset:56320
	global_load_lds_dwordx4 v150, s[98:99]
	s_add_i32 m0, s44, 0x2000
	s_add_u32 s42, s42, 0x80080
	s_addc_u32 s43, s43, 0
	s_add_i32 s44, s79, s49
	global_load_lds_dwordx4 v146, s[98:99]
	s_mov_b32 m0, s44
	s_nop 0
	global_load_lds_dwordx4 v150, s[42:43]
	s_add_i32 m0, s44, 0x2000
	s_nop 0
	global_load_lds_dwordx4 v146, s[42:43]
	s_mov_b32 m0, s59
	s_nop 0
	global_load_lds_dwordx4 v152, s[100:101]
	s_mov_b32 m0, s60
	s_nop 0
	global_load_lds_dwordx4 v148, s[100:101]
	s_waitcnt vmcnt(8)
	s_waitcnt lgkmcnt(0)
	s_barrier
	s_setprio 1
	s_waitcnt lgkmcnt(0)
	v_mfma_f32_16x16x32_bf16 v[62:65], v[130:133], v[192:195], v[62:65]
	v_mfma_f32_16x16x32_bf16 v[58:61], v[138:141], v[192:195], v[58:61]
	v_mfma_f32_16x16x32_bf16 v[54:57], v[130:133], v[200:203], v[54:57]
	v_mfma_f32_16x16x32_bf16 v[46:49], v[138:141], v[200:203], v[46:49]
	v_mfma_f32_16x16x32_bf16 v[38:41], v[130:133], v[208:211], v[38:41]
	v_mfma_f32_16x16x32_bf16 v[30:33], v[138:141], v[208:211], v[30:33]
	v_mfma_f32_16x16x32_bf16 v[22:25], v[130:133], v[216:219], v[22:25]
	v_mfma_f32_16x16x32_bf16 v[14:17], v[138:141], v[216:219], v[14:17]
	v_mfma_f32_16x16x32_bf16 v[62:65], v[134:137], v[196:199], v[62:65]
	v_mfma_f32_16x16x32_bf16 v[58:61], v[142:145], v[196:199], v[58:61]
	v_mfma_f32_16x16x32_bf16 v[54:57], v[134:137], v[204:207], v[54:57]
	v_mfma_f32_16x16x32_bf16 v[46:49], v[142:145], v[204:207], v[46:49]
	v_mfma_f32_16x16x32_bf16 v[38:41], v[134:137], v[212:215], v[38:41]
	v_mfma_f32_16x16x32_bf16 v[30:33], v[142:145], v[212:215], v[30:33]
	v_mfma_f32_16x16x32_bf16 v[22:25], v[134:137], v[220:223], v[22:25]
	v_mfma_f32_16x16x32_bf16 v[14:17], v[142:145], v[220:223], v[14:17]
	s_setprio 0
	s_setprio 1
	v_mfma_f32_16x16x32_bf16 v[50:53], v[166:169], v[192:195], v[50:53]
	v_mfma_f32_16x16x32_bf16 v[42:45], v[184:187], v[192:195], v[42:45]
	v_mfma_f32_16x16x32_bf16 v[34:37], v[166:169], v[200:203], v[34:37]
	v_mfma_f32_16x16x32_bf16 v[26:29], v[184:187], v[200:203], v[26:29]
	v_mfma_f32_16x16x32_bf16 v[18:21], v[166:169], v[208:211], v[18:21]
	v_mfma_f32_16x16x32_bf16 v[10:13], v[184:187], v[208:211], v[10:13]
	v_mfma_f32_16x16x32_bf16 v[6:9], v[166:169], v[216:219], v[6:9]
	v_mfma_f32_16x16x32_bf16 v[2:5], v[184:187], v[216:219], v[2:5]
	v_mfma_f32_16x16x32_bf16 v[50:53], v[170:173], v[196:199], v[50:53]
	v_mfma_f32_16x16x32_bf16 v[42:45], v[188:191], v[196:199], v[42:45]
	v_mfma_f32_16x16x32_bf16 v[34:37], v[170:173], v[204:207], v[34:37]
	v_mfma_f32_16x16x32_bf16 v[26:29], v[188:191], v[204:207], v[26:29]
	v_mfma_f32_16x16x32_bf16 v[18:21], v[170:173], v[212:215], v[18:21]
	v_mfma_f32_16x16x32_bf16 v[10:13], v[188:191], v[212:215], v[10:13]
	v_mfma_f32_16x16x32_bf16 v[6:9], v[170:173], v[220:223], v[6:9]
	v_mfma_f32_16x16x32_bf16 v[2:5], v[188:191], v[220:223], v[2:5]
	s_setprio 0
	s_barrier
	s_add_i32 s77, s77, 2
	s_add_u32 s40, s40, 0x100
	s_addc_u32 s41, s41, 0
	s_add_u32 s75, s75, 0x100
	s_addc_u32 s76, s76, 0
	s_cmp_gt_u32 s77, 29
	s_cbranch_scc0 .LBB0_90
	s_and_b64 vcc, exec, s[12:13]
	s_cbranch_vccnz .LBB0_95
	v_lshl_add_u32 v166, s38, 8, v1
	s_cmp_gt_i32 s73, 11
	s_mov_b64 s[38:39], -1
	s_cbranch_scc1 .LBB0_96

.LBB0_263:
	ds_read_b128 v[154:157], v184
	ds_read_b128 v[158:161], v184 offset:1024
	ds_read_b128 v[162:165], v184 offset:2048
	ds_read_b128 v[166:169], v184 offset:3072
	ds_read_b128 v[188:191], v185
	ds_read_b128 v[192:195], v185 offset:1024
	ds_read_b128 v[196:199], v185 offset:2048
	ds_read_b128 v[200:203], v185 offset:3072
	s_add_u32 s22, s20, 0xfffd0080
	s_addc_u32 s23, s21, -1
	s_cmp_eq_u32 s53, 8
	s_cselect_b32 s25, s1, s23
	s_cselect_b32 s24, s0, s22
	s_cselect_b32 s23, s19, s52
	s_cselect_b32 s22, s18, s51
	s_add_i32 m0, s31, 0xc000
	ds_read_b128 v[204:207], v186
	ds_read_b128 v[208:211], v186 offset:1024
	ds_read_b128 v[212:215], v186 offset:2048
	ds_read_b128 v[216:219], v186 offset:3072
	ds_read_b128 v[220:223], v186 offset:4096
	ds_read_b128 v[224:227], v186 offset:5120
	ds_read_b128 v[228:231], v186 offset:6144
	ds_read_b128 v[232:235], v186 offset:7168
	global_load_lds_dwordx4 v146, s[20:21]
	s_add_i32 m0, s31, 0xe000
	s_nop 0
	global_load_lds_dwordx4 v148, s[20:21]
	s_waitcnt vmcnt(8)
	s_waitcnt lgkmcnt(0)
	s_barrier
	s_setprio 1
	s_waitcnt lgkmcnt(0)
	v_mfma_f32_16x16x32_bf16 v[126:129], v[154:157], v[204:207], v[126:129]
	v_mfma_f32_16x16x32_bf16 v[122:125], v[162:165], v[204:207], v[122:125]
	v_mfma_f32_16x16x32_bf16 v[118:121], v[154:157], v[212:215], v[118:121]
	v_mfma_f32_16x16x32_bf16 v[110:113], v[162:165], v[212:215], v[110:113]
	v_mfma_f32_16x16x32_bf16 v[102:105], v[154:157], v[220:223], v[102:105]
	v_mfma_f32_16x16x32_bf16 v[94:97], v[162:165], v[220:223], v[94:97]
	v_mfma_f32_16x16x32_bf16 v[86:89], v[154:157], v[228:231], v[86:89]
	v_mfma_f32_16x16x32_bf16 v[78:81], v[162:165], v[228:231], v[78:81]
	v_mfma_f32_16x16x32_bf16 v[126:129], v[158:161], v[208:211], v[126:129]
	v_mfma_f32_16x16x32_bf16 v[122:125], v[166:169], v[208:211], v[122:125]
	v_mfma_f32_16x16x32_bf16 v[118:121], v[158:161], v[216:219], v[118:121]
	v_mfma_f32_16x16x32_bf16 v[110:113], v[166:169], v[216:219], v[110:113]
	v_mfma_f32_16x16x32_bf16 v[102:105], v[158:161], v[224:227], v[102:105]
	v_mfma_f32_16x16x32_bf16 v[94:97], v[166:169], v[224:227], v[94:97]
	v_mfma_f32_16x16x32_bf16 v[86:89], v[158:161], v[232:235], v[86:89]
	v_mfma_f32_16x16x32_bf16 v[78:81], v[166:169], v[232:235], v[78:81]
	s_setprio 0
	s_setprio 1
	v_mfma_f32_16x16x32_bf16 v[114:117], v[188:191], v[204:207], v[114:117]
	v_mfma_f32_16x16x32_bf16 v[106:109], v[196:199], v[204:207], v[106:109]
	v_mfma_f32_16x16x32_bf16 v[98:101], v[188:191], v[212:215], v[98:101]
	v_mfma_f32_16x16x32_bf16 v[90:93], v[196:199], v[212:215], v[90:93]
	v_mfma_f32_16x16x32_bf16 v[82:85], v[188:191], v[220:223], v[82:85]
	v_mfma_f32_16x16x32_bf16 v[74:77], v[196:199], v[220:223], v[74:77]
	v_mfma_f32_16x16x32_bf16 v[70:73], v[188:191], v[228:231], v[70:73]
	v_mfma_f32_16x16x32_bf16 v[66:69], v[196:199], v[228:231], v[66:69]
	v_mfma_f32_16x16x32_bf16 v[114:117], v[192:195], v[208:211], v[114:117]
	v_mfma_f32_16x16x32_bf16 v[106:109], v[200:203], v[208:211], v[106:109]
	v_mfma_f32_16x16x32_bf16 v[98:101], v[192:195], v[216:219], v[98:101]
	v_mfma_f32_16x16x32_bf16 v[90:93], v[200:203], v[216:219], v[90:93]
	v_mfma_f32_16x16x32_bf16 v[82:85], v[192:195], v[224:227], v[82:85]
	v_mfma_f32_16x16x32_bf16 v[74:77], v[200:203], v[224:227], v[74:77]
	v_mfma_f32_16x16x32_bf16 v[70:73], v[192:195], v[232:235], v[70:73]
	v_mfma_f32_16x16x32_bf16 v[66:69], v[200:203], v[232:235], v[66:69]
	s_setprio 0
	s_barrier
	s_add_i32 s54, s42, s29
	s_mov_b32 m0, s54
	ds_read_b128 v[204:207], v186 offset:16384
	ds_read_b128 v[208:211], v186 offset:17408
	ds_read_b128 v[212:215], v186 offset:18432
	ds_read_b128 v[216:219], v186 offset:19456
	ds_read_b128 v[220:223], v186 offset:20480
	ds_read_b128 v[224:227], v186 offset:21504
	ds_read_b128 v[228:231], v186 offset:22528
	ds_read_b128 v[232:235], v186 offset:23552
	global_load_lds_dwordx4 v136, s[22:23]
	s_add_u32 s98, s22, 0x80
	s_addc_u32 s99, s23, 0
	s_add_i32 m0, s54, 0x2000
	s_add_u32 s54, s22, 0x30000
	s_addc_u32 s55, s23, 0
	s_add_i32 s56, s43, s29
	global_load_lds_dwordx4 v132, s[22:23]
	s_mov_b32 m0, s56
	s_nop 0
	global_load_lds_dwordx4 v136, s[54:55]
	s_add_i32 m0, s56, 0x2000
	s_nop 0
	global_load_lds_dwordx4 v132, s[54:55]
	s_mov_b32 m0, s31
	s_nop 0
	global_load_lds_dwordx4 v138, s[24:25]
	s_mov_b32 m0, s33
	s_nop 0
	global_load_lds_dwordx4 v134, s[24:25]
	s_waitcnt vmcnt(8)
	s_waitcnt lgkmcnt(0)
	s_barrier
	s_setprio 1
	s_waitcnt lgkmcnt(0)
	v_mfma_f32_16x16x32_bf16 v[62:65], v[154:157], v[204:207], v[62:65]
	v_mfma_f32_16x16x32_bf16 v[58:61], v[162:165], v[204:207], v[58:61]
	v_mfma_f32_16x16x32_bf16 v[54:57], v[154:157], v[212:215], v[54:57]
	v_mfma_f32_16x16x32_bf16 v[46:49], v[162:165], v[212:215], v[46:49]
	v_mfma_f32_16x16x32_bf16 v[38:41], v[154:157], v[220:223], v[38:41]
	v_mfma_f32_16x16x32_bf16 v[30:33], v[162:165], v[220:223], v[30:33]
	v_mfma_f32_16x16x32_bf16 v[22:25], v[154:157], v[228:231], v[22:25]
	v_mfma_f32_16x16x32_bf16 v[14:17], v[162:165], v[228:231], v[14:17]
	v_mfma_f32_16x16x32_bf16 v[62:65], v[158:161], v[208:211], v[62:65]
	v_mfma_f32_16x16x32_bf16 v[58:61], v[166:169], v[208:211], v[58:61]
	v_mfma_f32_16x16x32_bf16 v[54:57], v[158:161], v[216:219], v[54:57]
	v_mfma_f32_16x16x32_bf16 v[46:49], v[166:169], v[216:219], v[46:49]
	v_mfma_f32_16x16x32_bf16 v[38:41], v[158:161], v[224:227], v[38:41]
	v_mfma_f32_16x16x32_bf16 v[30:33], v[166:169], v[224:227], v[30:33]
	v_mfma_f32_16x16x32_bf16 v[22:25], v[158:161], v[232:235], v[22:25]
	v_mfma_f32_16x16x32_bf16 v[14:17], v[166:169], v[232:235], v[14:17]
	s_setprio 0
	s_setprio 1
	v_mfma_f32_16x16x32_bf16 v[50:53], v[188:191], v[204:207], v[50:53]
	v_mfma_f32_16x16x32_bf16 v[42:45], v[196:199], v[204:207], v[42:45]
	v_mfma_f32_16x16x32_bf16 v[34:37], v[188:191], v[212:215], v[34:37]
	v_mfma_f32_16x16x32_bf16 v[26:29], v[196:199], v[212:215], v[26:29]
	v_mfma_f32_16x16x32_bf16 v[18:21], v[188:191], v[220:223], v[18:21]
	v_mfma_f32_16x16x32_bf16 v[10:13], v[196:199], v[220:223], v[10:13]
	v_mfma_f32_16x16x32_bf16 v[6:9], v[188:191], v[228:231], v[6:9]
	v_mfma_f32_16x16x32_bf16 v[2:5], v[196:199], v[228:231], v[2:5]
	v_mfma_f32_16x16x32_bf16 v[50:53], v[192:195], v[208:211], v[50:53]
	v_mfma_f32_16x16x32_bf16 v[42:45], v[200:203], v[208:211], v[42:45]
	v_mfma_f32_16x16x32_bf16 v[34:37], v[192:195], v[216:219], v[34:37]
	v_mfma_f32_16x16x32_bf16 v[26:29], v[200:203], v[216:219], v[26:29]
	v_mfma_f32_16x16x32_bf16 v[18:21], v[192:195], v[224:227], v[18:21]
	v_mfma_f32_16x16x32_bf16 v[10:13], v[200:203], v[224:227], v[10:13]
	v_mfma_f32_16x16x32_bf16 v[6:9], v[192:195], v[232:235], v[6:9]
	v_mfma_f32_16x16x32_bf16 v[2:5], v[200:203], v[232:235], v[2:5]
	s_setprio 0
	s_barrier
	s_add_u32 s100, s24, 0x80
	s_addc_u32 s101, s25, 0
	s_add_i32 s54, 0, 0x18000
	s_add_i32 s55, 0, 0x1c000
	v_add_u32_e32 v166, s54, v183
	v_add_u32_e32 v187, s55, v183
	ds_read_b128 v[154:157], v166
	ds_read_b128 v[158:161], v166 offset:1024
	ds_read_b128 v[162:165], v166 offset:2048
	ds_read_b128 v[166:169], v166 offset:3072
	ds_read_b128 v[188:191], v187
	ds_read_b128 v[192:195], v187 offset:1024
	ds_read_b128 v[196:199], v187 offset:2048
	ds_read_b128 v[200:203], v187 offset:3072
	s_add_u32 s24, s24, 0x30000
	s_addc_u32 s25, s25, 0
	s_mov_b32 m0, s34
	ds_read_b128 v[204:207], v186 offset:32768
	ds_read_b128 v[208:211], v186 offset:33792
	ds_read_b128 v[212:215], v186 offset:34816
	ds_read_b128 v[216:219], v186 offset:35840
	ds_read_b128 v[220:223], v186 offset:36864
	ds_read_b128 v[224:227], v186 offset:37888
	ds_read_b128 v[228:231], v186 offset:38912
	ds_read_b128 v[232:235], v186 offset:39936
	global_load_lds_dwordx4 v138, s[24:25]
	s_mov_b32 m0, s35
	s_nop 0
	global_load_lds_dwordx4 v134, s[24:25]
	s_waitcnt vmcnt(8)
	s_waitcnt lgkmcnt(0)
	s_barrier
	s_setprio 1
	s_waitcnt lgkmcnt(0)
	v_mfma_f32_16x16x32_bf16 v[126:129], v[154:157], v[204:207], v[126:129]
	v_mfma_f32_16x16x32_bf16 v[122:125], v[162:165], v[204:207], v[122:125]
	v_mfma_f32_16x16x32_bf16 v[118:121], v[154:157], v[212:215], v[118:121]
	v_mfma_f32_16x16x32_bf16 v[110:113], v[162:165], v[212:215], v[110:113]
	v_mfma_f32_16x16x32_bf16 v[102:105], v[154:157], v[220:223], v[102:105]
	v_mfma_f32_16x16x32_bf16 v[94:97], v[162:165], v[220:223], v[94:97]
	v_mfma_f32_16x16x32_bf16 v[86:89], v[154:157], v[228:231], v[86:89]
	v_mfma_f32_16x16x32_bf16 v[78:81], v[162:165], v[228:231], v[78:81]
	v_mfma_f32_16x16x32_bf16 v[126:129], v[158:161], v[208:211], v[126:129]
	v_mfma_f32_16x16x32_bf16 v[122:125], v[166:169], v[208:211], v[122:125]
	v_mfma_f32_16x16x32_bf16 v[118:121], v[158:161], v[216:219], v[118:121]
	v_mfma_f32_16x16x32_bf16 v[110:113], v[166:169], v[216:219], v[110:113]
	v_mfma_f32_16x16x32_bf16 v[102:105], v[158:161], v[224:227], v[102:105]
	v_mfma_f32_16x16x32_bf16 v[94:97], v[166:169], v[224:227], v[94:97]
	v_mfma_f32_16x16x32_bf16 v[86:89], v[158:161], v[232:235], v[86:89]
	v_mfma_f32_16x16x32_bf16 v[78:81], v[166:169], v[232:235], v[78:81]
	s_setprio 0
	s_setprio 1
	v_mfma_f32_16x16x32_bf16 v[114:117], v[188:191], v[204:207], v[114:117]
	v_mfma_f32_16x16x32_bf16 v[106:109], v[196:199], v[204:207], v[106:109]
	v_mfma_f32_16x16x32_bf16 v[98:101], v[188:191], v[212:215], v[98:101]
	v_mfma_f32_16x16x32_bf16 v[90:93], v[196:199], v[212:215], v[90:93]
	v_mfma_f32_16x16x32_bf16 v[82:85], v[188:191], v[220:223], v[82:85]
	v_mfma_f32_16x16x32_bf16 v[74:77], v[196:199], v[220:223], v[74:77]
	v_mfma_f32_16x16x32_bf16 v[70:73], v[188:191], v[228:231], v[70:73]
	v_mfma_f32_16x16x32_bf16 v[66:69], v[196:199], v[228:231], v[66:69]
	v_mfma_f32_16x16x32_bf16 v[114:117], v[192:195], v[208:211], v[114:117]
	v_mfma_f32_16x16x32_bf16 v[106:109], v[200:203], v[208:211], v[106:109]
	v_mfma_f32_16x16x32_bf16 v[98:101], v[192:195], v[216:219], v[98:101]
	v_mfma_f32_16x16x32_bf16 v[90:93], v[200:203], v[216:219], v[90:93]
	v_mfma_f32_16x16x32_bf16 v[82:85], v[192:195], v[224:227], v[82:85]
	v_mfma_f32_16x16x32_bf16 v[74:77], v[200:203], v[224:227], v[74:77]
	v_mfma_f32_16x16x32_bf16 v[70:73], v[192:195], v[232:235], v[70:73]
	v_mfma_f32_16x16x32_bf16 v[66:69], v[200:203], v[232:235], v[66:69]
	s_setprio 0
	s_barrier
	s_add_i32 s24, s54, s29
	s_mov_b32 m0, s24
	ds_read_b128 v[204:207], v186 offset:49152
	ds_read_b128 v[208:211], v186 offset:50176
	ds_read_b128 v[212:215], v186 offset:51200
	ds_read_b128 v[216:219], v186 offset:52224
	ds_read_b128 v[220:223], v186 offset:53248
	ds_read_b128 v[224:227], v186 offset:54272
	ds_read_b128 v[228:231], v186 offset:55296
	ds_read_b128 v[232:235], v186 offset:56320
	global_load_lds_dwordx4 v136, s[98:99]
	s_add_i32 m0, s24, 0x2000
	s_add_u32 s22, s22, 0x30080
	s_addc_u32 s23, s23, 0
	s_add_i32 s24, s55, s29
	global_load_lds_dwordx4 v132, s[98:99]
	s_mov_b32 m0, s24
	s_nop 0
	global_load_lds_dwordx4 v136, s[22:23]
	s_add_i32 m0, s24, 0x2000
	s_nop 0
	global_load_lds_dwordx4 v132, s[22:23]
	s_mov_b32 m0, s36
	s_nop 0
	global_load_lds_dwordx4 v138, s[100:101]
	s_mov_b32 m0, s37
	s_nop 0
	global_load_lds_dwordx4 v134, s[100:101]
	s_waitcnt vmcnt(8)
	s_waitcnt lgkmcnt(0)
	s_barrier
	s_setprio 1
	s_waitcnt lgkmcnt(0)
	v_mfma_f32_16x16x32_bf16 v[62:65], v[154:157], v[204:207], v[62:65]
	v_mfma_f32_16x16x32_bf16 v[58:61], v[162:165], v[204:207], v[58:61]
	v_mfma_f32_16x16x32_bf16 v[54:57], v[154:157], v[212:215], v[54:57]
	v_mfma_f32_16x16x32_bf16 v[46:49], v[162:165], v[212:215], v[46:49]
	v_mfma_f32_16x16x32_bf16 v[38:41], v[154:157], v[220:223], v[38:41]
	v_mfma_f32_16x16x32_bf16 v[30:33], v[162:165], v[220:223], v[30:33]
	v_mfma_f32_16x16x32_bf16 v[22:25], v[154:157], v[228:231], v[22:25]
	v_mfma_f32_16x16x32_bf16 v[14:17], v[162:165], v[228:231], v[14:17]
	v_mfma_f32_16x16x32_bf16 v[62:65], v[158:161], v[208:211], v[62:65]
	v_mfma_f32_16x16x32_bf16 v[58:61], v[166:169], v[208:211], v[58:61]
	v_mfma_f32_16x16x32_bf16 v[54:57], v[158:161], v[216:219], v[54:57]
	v_mfma_f32_16x16x32_bf16 v[46:49], v[166:169], v[216:219], v[46:49]
	v_mfma_f32_16x16x32_bf16 v[38:41], v[158:161], v[224:227], v[38:41]
	v_mfma_f32_16x16x32_bf16 v[30:33], v[166:169], v[224:227], v[30:33]
	v_mfma_f32_16x16x32_bf16 v[22:25], v[158:161], v[232:235], v[22:25]
	v_mfma_f32_16x16x32_bf16 v[14:17], v[166:169], v[232:235], v[14:17]
	s_setprio 0
	s_setprio 1
	v_mfma_f32_16x16x32_bf16 v[50:53], v[188:191], v[204:207], v[50:53]
	v_mfma_f32_16x16x32_bf16 v[42:45], v[196:199], v[204:207], v[42:45]
	v_mfma_f32_16x16x32_bf16 v[34:37], v[188:191], v[212:215], v[34:37]
	v_mfma_f32_16x16x32_bf16 v[26:29], v[196:199], v[212:215], v[26:29]
	v_mfma_f32_16x16x32_bf16 v[18:21], v[188:191], v[220:223], v[18:21]
	v_mfma_f32_16x16x32_bf16 v[10:13], v[196:199], v[220:223], v[10:13]
	v_mfma_f32_16x16x32_bf16 v[6:9], v[188:191], v[228:231], v[6:9]
	v_mfma_f32_16x16x32_bf16 v[2:5], v[196:199], v[228:231], v[2:5]
	v_mfma_f32_16x16x32_bf16 v[50:53], v[192:195], v[208:211], v[50:53]
	v_mfma_f32_16x16x32_bf16 v[42:45], v[200:203], v[208:211], v[42:45]
	v_mfma_f32_16x16x32_bf16 v[34:37], v[192:195], v[216:219], v[34:37]
	v_mfma_f32_16x16x32_bf16 v[26:29], v[200:203], v[216:219], v[26:29]
	v_mfma_f32_16x16x32_bf16 v[18:21], v[192:195], v[224:227], v[18:21]
	v_mfma_f32_16x16x32_bf16 v[10:13], v[200:203], v[224:227], v[10:13]
	v_mfma_f32_16x16x32_bf16 v[6:9], v[192:195], v[232:235], v[6:9]
	v_mfma_f32_16x16x32_bf16 v[2:5], v[200:203], v[232:235], v[2:5]
	s_setprio 0
	s_barrier
	s_add_i32 s53, s53, 2
	s_add_u32 s20, s20, 0x100
	s_addc_u32 s21, s21, 0
	s_add_u32 s51, s51, 0x100
	s_addc_u32 s52, s52, 0
	s_cmp_gt_u32 s53, 9
	s_cbranch_scc0 .LBB0_263
	s_and_b64 vcc, exec, s[14:15]
	s_cbranch_vccz .LBB0_266
	s_barrier

.LBB0_291:
	ds_read_b128 v[154:157], v1
	ds_read_b128 v[158:161], v1 offset:1024
	ds_read_b128 v[162:165], v1 offset:2048
	ds_read_b128 v[166:169], v1 offset:3072
	ds_read_b128 v[170:173], v151
	ds_read_b128 v[174:177], v151 offset:1024
	ds_read_b128 v[178:181], v151 offset:2048
	ds_read_b128 v[182:185], v151 offset:3072
	s_add_u32 s30, s28, 0xfffe0080
	s_addc_u32 s31, s29, -1
	s_cmp_eq_u32 s64, 4
	s_cselect_b32 s35, s23, s31
	s_cselect_b32 s34, s60, s30
	s_cselect_b32 s31, s21, s63
	s_cselect_b32 s30, s61, s62
	s_add_i32 m0, s19, 0xc000
	ds_read_b128 v[186:189], v152
	ds_read_b128 v[190:193], v152 offset:1024
	ds_read_b128 v[194:197], v152 offset:2048
	ds_read_b128 v[198:201], v152 offset:3072
	ds_read_b128 v[202:205], v152 offset:4096
	ds_read_b128 v[206:209], v152 offset:5120
	ds_read_b128 v[210:213], v152 offset:6144
	ds_read_b128 v[214:217], v152 offset:7168
	global_load_lds_dwordx4 v140, s[28:29]
	s_add_i32 m0, s19, 0xe000
	s_nop 0
	global_load_lds_dwordx4 v142, s[28:29]
	s_waitcnt vmcnt(8)
	s_waitcnt lgkmcnt(0)
	s_barrier
	s_setprio 1
	s_waitcnt lgkmcnt(0)
	v_mfma_f32_16x16x32_bf16 v[126:129], v[154:157], v[186:189], v[126:129]
	v_mfma_f32_16x16x32_bf16 v[122:125], v[162:165], v[186:189], v[122:125]
	v_mfma_f32_16x16x32_bf16 v[118:121], v[154:157], v[194:197], v[118:121]
	v_mfma_f32_16x16x32_bf16 v[114:117], v[162:165], v[194:197], v[114:117]
	v_mfma_f32_16x16x32_bf16 v[102:105], v[154:157], v[202:205], v[102:105]
	v_mfma_f32_16x16x32_bf16 v[98:101], v[162:165], v[202:205], v[98:101]
	v_mfma_f32_16x16x32_bf16 v[86:89], v[154:157], v[210:213], v[86:89]
	v_mfma_f32_16x16x32_bf16 v[82:85], v[162:165], v[210:213], v[82:85]
	v_mfma_f32_16x16x32_bf16 v[126:129], v[158:161], v[190:193], v[126:129]
	v_mfma_f32_16x16x32_bf16 v[122:125], v[166:169], v[190:193], v[122:125]
	v_mfma_f32_16x16x32_bf16 v[118:121], v[158:161], v[198:201], v[118:121]
	v_mfma_f32_16x16x32_bf16 v[114:117], v[166:169], v[198:201], v[114:117]
	v_mfma_f32_16x16x32_bf16 v[102:105], v[158:161], v[206:209], v[102:105]
	v_mfma_f32_16x16x32_bf16 v[98:101], v[166:169], v[206:209], v[98:101]
	v_mfma_f32_16x16x32_bf16 v[86:89], v[158:161], v[214:217], v[86:89]
	v_mfma_f32_16x16x32_bf16 v[82:85], v[166:169], v[214:217], v[82:85]
	s_setprio 0
	s_setprio 1
	v_mfma_f32_16x16x32_bf16 v[110:113], v[170:173], v[186:189], v[110:113]
	v_mfma_f32_16x16x32_bf16 v[106:109], v[178:181], v[186:189], v[106:109]
	v_mfma_f32_16x16x32_bf16 v[94:97], v[170:173], v[194:197], v[94:97]
	v_mfma_f32_16x16x32_bf16 v[90:93], v[178:181], v[194:197], v[90:93]
	v_mfma_f32_16x16x32_bf16 v[78:81], v[170:173], v[202:205], v[78:81]
	v_mfma_f32_16x16x32_bf16 v[74:77], v[178:181], v[202:205], v[74:77]
	v_mfma_f32_16x16x32_bf16 v[70:73], v[170:173], v[210:213], v[70:73]
	v_mfma_f32_16x16x32_bf16 v[66:69], v[178:181], v[210:213], v[66:69]
	v_mfma_f32_16x16x32_bf16 v[110:113], v[174:177], v[190:193], v[110:113]
	v_mfma_f32_16x16x32_bf16 v[106:109], v[182:185], v[190:193], v[106:109]
	v_mfma_f32_16x16x32_bf16 v[94:97], v[174:177], v[198:201], v[94:97]
	v_mfma_f32_16x16x32_bf16 v[90:93], v[182:185], v[198:201], v[90:93]
	v_mfma_f32_16x16x32_bf16 v[78:81], v[174:177], v[206:209], v[78:81]
	v_mfma_f32_16x16x32_bf16 v[74:77], v[182:185], v[206:209], v[74:77]
	v_mfma_f32_16x16x32_bf16 v[70:73], v[174:177], v[214:217], v[70:73]
	v_mfma_f32_16x16x32_bf16 v[66:69], v[182:185], v[214:217], v[66:69]
	s_setprio 0
	s_barrier
	s_add_i32 s65, s53, s40
	s_mov_b32 m0, s65
	ds_read_b128 v[186:189], v152 offset:16384
	ds_read_b128 v[190:193], v152 offset:17408
	ds_read_b128 v[194:197], v152 offset:18432
	ds_read_b128 v[198:201], v152 offset:19456
	ds_read_b128 v[202:205], v152 offset:20480
	ds_read_b128 v[206:209], v152 offset:21504
	ds_read_b128 v[210:213], v152 offset:22528
	ds_read_b128 v[214:217], v152 offset:23552
	global_load_lds_dwordx4 v134, s[30:31]
	s_add_u32 s98, s30, 0x80
	s_addc_u32 s99, s31, 0
	s_add_i32 m0, s65, 0x2000
	s_add_u32 s66, s30, 0x20000
	s_addc_u32 s67, s31, 0
	s_add_i32 s65, s54, s40
	global_load_lds_dwordx4 v138, s[30:31]
	s_mov_b32 m0, s65
	s_nop 0
	global_load_lds_dwordx4 v134, s[66:67]
	s_add_i32 m0, s65, 0x2000
	s_nop 0
	global_load_lds_dwordx4 v138, s[66:67]
	s_mov_b32 m0, s19
	s_nop 0
	global_load_lds_dwordx4 v132, s[34:35]
	s_mov_b32 m0, s41
	s_nop 0
	global_load_lds_dwordx4 v136, s[34:35]
	s_waitcnt vmcnt(8)
	s_waitcnt lgkmcnt(0)
	s_barrier
	s_setprio 1
	s_waitcnt lgkmcnt(0)
	v_mfma_f32_16x16x32_bf16 v[62:65], v[154:157], v[186:189], v[62:65]
	v_mfma_f32_16x16x32_bf16 v[58:61], v[162:165], v[186:189], v[58:61]
	v_mfma_f32_16x16x32_bf16 v[54:57], v[154:157], v[194:197], v[54:57]
	v_mfma_f32_16x16x32_bf16 v[50:53], v[162:165], v[194:197], v[50:53]
	v_mfma_f32_16x16x32_bf16 v[38:41], v[154:157], v[202:205], v[38:41]
	v_mfma_f32_16x16x32_bf16 v[34:37], v[162:165], v[202:205], v[34:37]
	v_mfma_f32_16x16x32_bf16 v[22:25], v[154:157], v[210:213], v[22:25]
	v_mfma_f32_16x16x32_bf16 v[18:21], v[162:165], v[210:213], v[18:21]
	v_mfma_f32_16x16x32_bf16 v[62:65], v[158:161], v[190:193], v[62:65]
	v_mfma_f32_16x16x32_bf16 v[58:61], v[166:169], v[190:193], v[58:61]
	v_mfma_f32_16x16x32_bf16 v[54:57], v[158:161], v[198:201], v[54:57]
	v_mfma_f32_16x16x32_bf16 v[50:53], v[166:169], v[198:201], v[50:53]
	v_mfma_f32_16x16x32_bf16 v[38:41], v[158:161], v[206:209], v[38:41]
	v_mfma_f32_16x16x32_bf16 v[34:37], v[166:169], v[206:209], v[34:37]
	v_mfma_f32_16x16x32_bf16 v[22:25], v[158:161], v[214:217], v[22:25]
	v_mfma_f32_16x16x32_bf16 v[18:21], v[166:169], v[214:217], v[18:21]
	s_setprio 0
	s_setprio 1
	v_mfma_f32_16x16x32_bf16 v[46:49], v[170:173], v[186:189], v[46:49]
	v_mfma_f32_16x16x32_bf16 v[42:45], v[178:181], v[186:189], v[42:45]
	v_mfma_f32_16x16x32_bf16 v[30:33], v[170:173], v[194:197], v[30:33]
	v_mfma_f32_16x16x32_bf16 v[26:29], v[178:181], v[194:197], v[26:29]
	v_mfma_f32_16x16x32_bf16 v[14:17], v[170:173], v[202:205], v[14:17]
	v_mfma_f32_16x16x32_bf16 v[10:13], v[178:181], v[202:205], v[10:13]
	v_mfma_f32_16x16x32_bf16 v[6:9], v[170:173], v[210:213], v[6:9]
	v_mfma_f32_16x16x32_bf16 v[2:5], v[178:181], v[210:213], v[2:5]
	v_mfma_f32_16x16x32_bf16 v[46:49], v[174:177], v[190:193], v[46:49]
	v_mfma_f32_16x16x32_bf16 v[42:45], v[182:185], v[190:193], v[42:45]
	v_mfma_f32_16x16x32_bf16 v[30:33], v[174:177], v[198:201], v[30:33]
	v_mfma_f32_16x16x32_bf16 v[26:29], v[182:185], v[198:201], v[26:29]
	v_mfma_f32_16x16x32_bf16 v[14:17], v[174:177], v[206:209], v[14:17]
	v_mfma_f32_16x16x32_bf16 v[10:13], v[182:185], v[206:209], v[10:13]
	v_mfma_f32_16x16x32_bf16 v[6:9], v[174:177], v[214:217], v[6:9]
	v_mfma_f32_16x16x32_bf16 v[2:5], v[182:185], v[214:217], v[2:5]
	s_setprio 0
	s_barrier
	s_add_u32 s100, s34, 0x80
	s_addc_u32 s101, s35, 0
	s_add_i32 s65, 0, 0x18000
	v_add_u32_e32 v130, s65, v149
	s_add_i32 s66, 0, 0x1c000
	ds_read_b128 v[154:157], v130
	ds_read_b128 v[158:161], v130 offset:1024
	ds_read_b128 v[162:165], v130 offset:2048
	ds_read_b128 v[166:169], v130 offset:3072
	v_add_u32_e32 v130, s66, v149
	ds_read_b128 v[170:173], v130
	ds_read_b128 v[174:177], v130 offset:1024
	ds_read_b128 v[178:181], v130 offset:2048
	ds_read_b128 v[182:185], v130 offset:3072
	s_add_u32 s34, s34, 0x20000
	s_addc_u32 s35, s35, 0
	s_mov_b32 m0, s42
	ds_read_b128 v[186:189], v152 offset:32768
	ds_read_b128 v[190:193], v152 offset:33792
	ds_read_b128 v[194:197], v152 offset:34816
	ds_read_b128 v[198:201], v152 offset:35840
	ds_read_b128 v[202:205], v152 offset:36864
	ds_read_b128 v[206:209], v152 offset:37888
	ds_read_b128 v[210:213], v152 offset:38912
	ds_read_b128 v[214:217], v152 offset:39936
	global_load_lds_dwordx4 v132, s[34:35]
	s_mov_b32 m0, s43
	s_nop 0
	global_load_lds_dwordx4 v136, s[34:35]
	s_waitcnt vmcnt(8)
	s_waitcnt lgkmcnt(0)
	s_barrier
	s_setprio 1
	s_waitcnt lgkmcnt(0)
	v_mfma_f32_16x16x32_bf16 v[126:129], v[154:157], v[186:189], v[126:129]
	v_mfma_f32_16x16x32_bf16 v[122:125], v[162:165], v[186:189], v[122:125]
	v_mfma_f32_16x16x32_bf16 v[118:121], v[154:157], v[194:197], v[118:121]
	v_mfma_f32_16x16x32_bf16 v[114:117], v[162:165], v[194:197], v[114:117]
	v_mfma_f32_16x16x32_bf16 v[102:105], v[154:157], v[202:205], v[102:105]
	v_mfma_f32_16x16x32_bf16 v[98:101], v[162:165], v[202:205], v[98:101]
	v_mfma_f32_16x16x32_bf16 v[86:89], v[154:157], v[210:213], v[86:89]
	v_mfma_f32_16x16x32_bf16 v[82:85], v[162:165], v[210:213], v[82:85]
	v_mfma_f32_16x16x32_bf16 v[126:129], v[158:161], v[190:193], v[126:129]
	v_mfma_f32_16x16x32_bf16 v[122:125], v[166:169], v[190:193], v[122:125]
	v_mfma_f32_16x16x32_bf16 v[118:121], v[158:161], v[198:201], v[118:121]
	v_mfma_f32_16x16x32_bf16 v[114:117], v[166:169], v[198:201], v[114:117]
	v_mfma_f32_16x16x32_bf16 v[102:105], v[158:161], v[206:209], v[102:105]
	v_mfma_f32_16x16x32_bf16 v[98:101], v[166:169], v[206:209], v[98:101]
	v_mfma_f32_16x16x32_bf16 v[86:89], v[158:161], v[214:217], v[86:89]
	v_mfma_f32_16x16x32_bf16 v[82:85], v[166:169], v[214:217], v[82:85]
	s_setprio 0
	s_setprio 1
	v_mfma_f32_16x16x32_bf16 v[110:113], v[170:173], v[186:189], v[110:113]
	v_mfma_f32_16x16x32_bf16 v[106:109], v[178:181], v[186:189], v[106:109]
	v_mfma_f32_16x16x32_bf16 v[94:97], v[170:173], v[194:197], v[94:97]
	v_mfma_f32_16x16x32_bf16 v[90:93], v[178:181], v[194:197], v[90:93]
	v_mfma_f32_16x16x32_bf16 v[78:81], v[170:173], v[202:205], v[78:81]
	v_mfma_f32_16x16x32_bf16 v[74:77], v[178:181], v[202:205], v[74:77]
	v_mfma_f32_16x16x32_bf16 v[70:73], v[170:173], v[210:213], v[70:73]
	v_mfma_f32_16x16x32_bf16 v[66:69], v[178:181], v[210:213], v[66:69]
	v_mfma_f32_16x16x32_bf16 v[110:113], v[174:177], v[190:193], v[110:113]
	v_mfma_f32_16x16x32_bf16 v[106:109], v[182:185], v[190:193], v[106:109]
	v_mfma_f32_16x16x32_bf16 v[94:97], v[174:177], v[198:201], v[94:97]
	v_mfma_f32_16x16x32_bf16 v[90:93], v[182:185], v[198:201], v[90:93]
	v_mfma_f32_16x16x32_bf16 v[78:81], v[174:177], v[206:209], v[78:81]
	v_mfma_f32_16x16x32_bf16 v[74:77], v[182:185], v[206:209], v[74:77]
	v_mfma_f32_16x16x32_bf16 v[70:73], v[174:177], v[214:217], v[70:73]
	v_mfma_f32_16x16x32_bf16 v[66:69], v[182:185], v[214:217], v[66:69]
	s_setprio 0
	s_barrier
	s_add_i32 s34, s65, s40
	s_mov_b32 m0, s34
	ds_read_b128 v[186:189], v152 offset:49152
	ds_read_b128 v[190:193], v152 offset:50176
	ds_read_b128 v[194:197], v152 offset:51200
	ds_read_b128 v[198:201], v152 offset:52224
	ds_read_b128 v[202:205], v152 offset:53248
	ds_read_b128 v[206:209], v152 offset:54272
	ds_read_b128 v[210:213], v152 offset:55296
	ds_read_b128 v[214:217], v152 offset:56320
	global_load_lds_dwordx4 v134, s[98:99]
	s_add_i32 m0, s34, 0x2000
	s_add_u32 s30, s30, 0x20080
	s_addc_u32 s31, s31, 0
	s_add_i32 s34, s66, s40
	global_load_lds_dwordx4 v138, s[98:99]
	s_mov_b32 m0, s34
	s_nop 0
	global_load_lds_dwordx4 v134, s[30:31]
	s_add_i32 m0, s34, 0x2000
	s_nop 0
	global_load_lds_dwordx4 v138, s[30:31]
	s_mov_b32 m0, s49
	s_nop 0
	global_load_lds_dwordx4 v132, s[100:101]
	s_mov_b32 m0, s50
	s_nop 0
	global_load_lds_dwordx4 v136, s[100:101]
	s_waitcnt vmcnt(8)
	s_waitcnt lgkmcnt(0)
	s_barrier
	s_setprio 1
	s_waitcnt lgkmcnt(0)
	v_mfma_f32_16x16x32_bf16 v[62:65], v[154:157], v[186:189], v[62:65]
	v_mfma_f32_16x16x32_bf16 v[58:61], v[162:165], v[186:189], v[58:61]
	v_mfma_f32_16x16x32_bf16 v[54:57], v[154:157], v[194:197], v[54:57]
	v_mfma_f32_16x16x32_bf16 v[50:53], v[162:165], v[194:197], v[50:53]
	v_mfma_f32_16x16x32_bf16 v[38:41], v[154:157], v[202:205], v[38:41]
	v_mfma_f32_16x16x32_bf16 v[34:37], v[162:165], v[202:205], v[34:37]
	v_mfma_f32_16x16x32_bf16 v[22:25], v[154:157], v[210:213], v[22:25]
	v_mfma_f32_16x16x32_bf16 v[18:21], v[162:165], v[210:213], v[18:21]
	v_mfma_f32_16x16x32_bf16 v[62:65], v[158:161], v[190:193], v[62:65]
	v_mfma_f32_16x16x32_bf16 v[58:61], v[166:169], v[190:193], v[58:61]
	v_mfma_f32_16x16x32_bf16 v[54:57], v[158:161], v[198:201], v[54:57]
	v_mfma_f32_16x16x32_bf16 v[50:53], v[166:169], v[198:201], v[50:53]
	v_mfma_f32_16x16x32_bf16 v[38:41], v[158:161], v[206:209], v[38:41]
	v_mfma_f32_16x16x32_bf16 v[34:37], v[166:169], v[206:209], v[34:37]
	v_mfma_f32_16x16x32_bf16 v[22:25], v[158:161], v[214:217], v[22:25]
	v_mfma_f32_16x16x32_bf16 v[18:21], v[166:169], v[214:217], v[18:21]
	s_setprio 0
	s_setprio 1
	v_mfma_f32_16x16x32_bf16 v[46:49], v[170:173], v[186:189], v[46:49]
	v_mfma_f32_16x16x32_bf16 v[42:45], v[178:181], v[186:189], v[42:45]
	v_mfma_f32_16x16x32_bf16 v[30:33], v[170:173], v[194:197], v[30:33]
	v_mfma_f32_16x16x32_bf16 v[26:29], v[178:181], v[194:197], v[26:29]
	v_mfma_f32_16x16x32_bf16 v[14:17], v[170:173], v[202:205], v[14:17]
	v_mfma_f32_16x16x32_bf16 v[10:13], v[178:181], v[202:205], v[10:13]
	v_mfma_f32_16x16x32_bf16 v[6:9], v[170:173], v[210:213], v[6:9]
	v_mfma_f32_16x16x32_bf16 v[2:5], v[178:181], v[210:213], v[2:5]
	v_mfma_f32_16x16x32_bf16 v[46:49], v[174:177], v[190:193], v[46:49]
	v_mfma_f32_16x16x32_bf16 v[42:45], v[182:185], v[190:193], v[42:45]
	v_mfma_f32_16x16x32_bf16 v[30:33], v[174:177], v[198:201], v[30:33]
	v_mfma_f32_16x16x32_bf16 v[26:29], v[182:185], v[198:201], v[26:29]
	v_mfma_f32_16x16x32_bf16 v[14:17], v[174:177], v[206:209], v[14:17]
	v_mfma_f32_16x16x32_bf16 v[10:13], v[182:185], v[206:209], v[10:13]
	v_mfma_f32_16x16x32_bf16 v[6:9], v[174:177], v[214:217], v[6:9]
	v_mfma_f32_16x16x32_bf16 v[2:5], v[182:185], v[214:217], v[2:5]
	s_setprio 0
	s_barrier
	s_add_i32 s64, s64, 2
	s_add_u32 s28, s28, 0x100
	s_addc_u32 s29, s29, 0
	s_add_u32 s62, s62, 0x100
	s_addc_u32 s63, s63, 0
	s_cmp_gt_u32 s64, 5
	s_cbranch_scc0 .LBB0_291
	s_and_b64 vcc, exec, s[8:9]
	s_cbranch_vccz .LBB0_294
	s_barrier

.LBB0_531:
	ds_read_b128 v[146:149], v152
	ds_read_b128 v[156:159], v152 offset:1024
	ds_read_b128 v[160:163], v152 offset:2048
	ds_read_b128 v[164:167], v152 offset:3072
	ds_read_b128 v[168:171], v153
	ds_read_b128 v[172:175], v153 offset:1024
	ds_read_b128 v[176:179], v153 offset:2048
	ds_read_b128 v[180:183], v153 offset:3072
	s_add_u32 s22, s20, 0xfffc0080
	s_addc_u32 s23, s21, -1
	s_cmp_eq_u32 s46, 12
	s_cselect_b32 s25, s13, s23
	s_cselect_b32 s24, s42, s22
	s_cselect_b32 s23, s11, s45
	s_cselect_b32 s22, s43, s44
	s_add_i32 m0, s19, 0xc000
	ds_read_b128 v[184:187], v154
	ds_read_b128 v[188:191], v154 offset:1024
	ds_read_b128 v[192:195], v154 offset:2048
	ds_read_b128 v[196:199], v154 offset:3072
	ds_read_b128 v[200:203], v154 offset:4096
	ds_read_b128 v[204:207], v154 offset:5120
	ds_read_b128 v[208:211], v154 offset:6144
	ds_read_b128 v[212:215], v154 offset:7168
	global_load_lds_dwordx4 v138, s[20:21]
	s_add_i32 m0, s19, 0xe000
	s_nop 0
	global_load_lds_dwordx4 v140, s[20:21]
	s_waitcnt vmcnt(8)
	s_waitcnt lgkmcnt(0)
	s_barrier
	s_setprio 1
	s_waitcnt lgkmcnt(0)
	v_mfma_f32_16x16x32_bf16 v[126:129], v[146:149], v[184:187], v[126:129]
	v_mfma_f32_16x16x32_bf16 v[122:125], v[160:163], v[184:187], v[122:125]
	v_mfma_f32_16x16x32_bf16 v[110:113], v[146:149], v[192:195], v[110:113]
	v_mfma_f32_16x16x32_bf16 v[106:109], v[160:163], v[192:195], v[106:109]
	v_mfma_f32_16x16x32_bf16 v[94:97], v[146:149], v[200:203], v[94:97]
	v_mfma_f32_16x16x32_bf16 v[90:93], v[160:163], v[200:203], v[90:93]
	v_mfma_f32_16x16x32_bf16 v[78:81], v[146:149], v[208:211], v[78:81]
	v_mfma_f32_16x16x32_bf16 v[74:77], v[160:163], v[208:211], v[74:77]
	v_mfma_f32_16x16x32_bf16 v[126:129], v[156:159], v[188:191], v[126:129]
	v_mfma_f32_16x16x32_bf16 v[122:125], v[164:167], v[188:191], v[122:125]
	v_mfma_f32_16x16x32_bf16 v[110:113], v[156:159], v[196:199], v[110:113]
	v_mfma_f32_16x16x32_bf16 v[106:109], v[164:167], v[196:199], v[106:109]
	v_mfma_f32_16x16x32_bf16 v[94:97], v[156:159], v[204:207], v[94:97]
	v_mfma_f32_16x16x32_bf16 v[90:93], v[164:167], v[204:207], v[90:93]
	v_mfma_f32_16x16x32_bf16 v[78:81], v[156:159], v[212:215], v[78:81]
	v_mfma_f32_16x16x32_bf16 v[74:77], v[164:167], v[212:215], v[74:77]
	s_setprio 0
	s_setprio 1
	v_mfma_f32_16x16x32_bf16 v[118:121], v[168:171], v[184:187], v[118:121]
	v_mfma_f32_16x16x32_bf16 v[114:117], v[176:179], v[184:187], v[114:117]
	v_mfma_f32_16x16x32_bf16 v[102:105], v[168:171], v[192:195], v[102:105]
	v_mfma_f32_16x16x32_bf16 v[98:101], v[176:179], v[192:195], v[98:101]
	v_mfma_f32_16x16x32_bf16 v[86:89], v[168:171], v[200:203], v[86:89]
	v_mfma_f32_16x16x32_bf16 v[82:85], v[176:179], v[200:203], v[82:85]
	v_mfma_f32_16x16x32_bf16 v[70:73], v[168:171], v[208:211], v[70:73]
	v_mfma_f32_16x16x32_bf16 v[66:69], v[176:179], v[208:211], v[66:69]
	v_mfma_f32_16x16x32_bf16 v[118:121], v[172:175], v[188:191], v[118:121]
	v_mfma_f32_16x16x32_bf16 v[114:117], v[180:183], v[188:191], v[114:117]
	v_mfma_f32_16x16x32_bf16 v[102:105], v[172:175], v[196:199], v[102:105]
	v_mfma_f32_16x16x32_bf16 v[98:101], v[180:183], v[196:199], v[98:101]
	v_mfma_f32_16x16x32_bf16 v[86:89], v[172:175], v[204:207], v[86:89]
	v_mfma_f32_16x16x32_bf16 v[82:85], v[180:183], v[204:207], v[82:85]
	v_mfma_f32_16x16x32_bf16 v[70:73], v[172:175], v[212:215], v[70:73]
	v_mfma_f32_16x16x32_bf16 v[66:69], v[180:183], v[212:215], v[66:69]
	s_setprio 0
	s_barrier
	s_add_i32 s47, s39, s29
	s_mov_b32 m0, s47
	ds_read_b128 v[184:187], v154 offset:16384
	ds_read_b128 v[188:191], v154 offset:17408
	ds_read_b128 v[192:195], v154 offset:18432
	ds_read_b128 v[196:199], v154 offset:19456
	ds_read_b128 v[200:203], v154 offset:20480
	ds_read_b128 v[204:207], v154 offset:21504
	ds_read_b128 v[208:211], v154 offset:22528
	ds_read_b128 v[212:215], v154 offset:23552
	global_load_lds_dwordx4 v132, s[22:23]
	s_add_u32 s98, s22, 0x80
	s_addc_u32 s99, s23, 0
	s_add_i32 m0, s47, 0x2000
	s_add_u32 s48, s22, 0x40000
	s_addc_u32 s49, s23, 0
	s_add_i32 s47, s40, s29
	global_load_lds_dwordx4 v136, s[22:23]
	s_mov_b32 m0, s47
	s_nop 0
	global_load_lds_dwordx4 v132, s[48:49]
	s_add_i32 m0, s47, 0x2000
	s_nop 0
	global_load_lds_dwordx4 v136, s[48:49]
	s_mov_b32 m0, s19
	s_nop 0
	global_load_lds_dwordx4 v130, s[24:25]
	s_mov_b32 m0, s30
	s_nop 0
	global_load_lds_dwordx4 v134, s[24:25]
	s_waitcnt vmcnt(8)
	s_waitcnt lgkmcnt(0)
	s_barrier
	s_setprio 1
	s_waitcnt lgkmcnt(0)
	v_mfma_f32_16x16x32_bf16 v[62:65], v[146:149], v[184:187], v[62:65]
	v_mfma_f32_16x16x32_bf16 v[58:61], v[160:163], v[184:187], v[58:61]
	v_mfma_f32_16x16x32_bf16 v[46:49], v[146:149], v[192:195], v[46:49]
	v_mfma_f32_16x16x32_bf16 v[42:45], v[160:163], v[192:195], v[42:45]
	v_mfma_f32_16x16x32_bf16 v[30:33], v[146:149], v[200:203], v[30:33]
	v_mfma_f32_16x16x32_bf16 v[26:29], v[160:163], v[200:203], v[26:29]
	v_mfma_f32_16x16x32_bf16 v[14:17], v[146:149], v[208:211], v[14:17]
	v_mfma_f32_16x16x32_bf16 v[10:13], v[160:163], v[208:211], v[10:13]
	v_mfma_f32_16x16x32_bf16 v[62:65], v[156:159], v[188:191], v[62:65]
	v_mfma_f32_16x16x32_bf16 v[58:61], v[164:167], v[188:191], v[58:61]
	v_mfma_f32_16x16x32_bf16 v[46:49], v[156:159], v[196:199], v[46:49]
	v_mfma_f32_16x16x32_bf16 v[42:45], v[164:167], v[196:199], v[42:45]
	v_mfma_f32_16x16x32_bf16 v[30:33], v[156:159], v[204:207], v[30:33]
	v_mfma_f32_16x16x32_bf16 v[26:29], v[164:167], v[204:207], v[26:29]
	v_mfma_f32_16x16x32_bf16 v[14:17], v[156:159], v[212:215], v[14:17]
	v_mfma_f32_16x16x32_bf16 v[10:13], v[164:167], v[212:215], v[10:13]
	s_setprio 0
	s_setprio 1
	v_mfma_f32_16x16x32_bf16 v[54:57], v[168:171], v[184:187], v[54:57]
	v_mfma_f32_16x16x32_bf16 v[50:53], v[176:179], v[184:187], v[50:53]
	v_mfma_f32_16x16x32_bf16 v[38:41], v[168:171], v[192:195], v[38:41]
	v_mfma_f32_16x16x32_bf16 v[34:37], v[176:179], v[192:195], v[34:37]
	v_mfma_f32_16x16x32_bf16 v[22:25], v[168:171], v[200:203], v[22:25]
	v_mfma_f32_16x16x32_bf16 v[18:21], v[176:179], v[200:203], v[18:21]
	v_mfma_f32_16x16x32_bf16 v[6:9], v[168:171], v[208:211], v[6:9]
	v_mfma_f32_16x16x32_bf16 v[2:5], v[176:179], v[208:211], v[2:5]
	v_mfma_f32_16x16x32_bf16 v[54:57], v[172:175], v[188:191], v[54:57]
	v_mfma_f32_16x16x32_bf16 v[50:53], v[180:183], v[188:191], v[50:53]
	v_mfma_f32_16x16x32_bf16 v[38:41], v[172:175], v[196:199], v[38:41]
	v_mfma_f32_16x16x32_bf16 v[34:37], v[180:183], v[196:199], v[34:37]
	v_mfma_f32_16x16x32_bf16 v[22:25], v[172:175], v[204:207], v[22:25]
	v_mfma_f32_16x16x32_bf16 v[18:21], v[180:183], v[204:207], v[18:21]
	v_mfma_f32_16x16x32_bf16 v[6:9], v[172:175], v[212:215], v[6:9]
	v_mfma_f32_16x16x32_bf16 v[2:5], v[180:183], v[212:215], v[2:5]
	s_setprio 0
	s_barrier
	s_add_u32 s100, s24, 0x80
	s_addc_u32 s101, s25, 0
	s_add_i32 s47, 0, 0x18000
	v_add_u32_e32 v155, s47, v150
	s_add_i32 s48, 0, 0x1c000
	ds_read_b128 v[146:149], v155
	ds_read_b128 v[156:159], v155 offset:1024
	ds_read_b128 v[160:163], v155 offset:2048
	ds_read_b128 v[164:167], v155 offset:3072
	v_add_u32_e32 v155, s48, v150
	ds_read_b128 v[168:171], v155
	ds_read_b128 v[172:175], v155 offset:1024
	ds_read_b128 v[176:179], v155 offset:2048
	ds_read_b128 v[180:183], v155 offset:3072
	s_add_u32 s24, s24, 0x40000
	s_addc_u32 s25, s25, 0
	s_mov_b32 m0, s31
	ds_read_b128 v[184:187], v154 offset:32768
	ds_read_b128 v[188:191], v154 offset:33792
	ds_read_b128 v[192:195], v154 offset:34816
	ds_read_b128 v[196:199], v154 offset:35840
	ds_read_b128 v[200:203], v154 offset:36864
	ds_read_b128 v[204:207], v154 offset:37888
	ds_read_b128 v[208:211], v154 offset:38912
	ds_read_b128 v[212:215], v154 offset:39936
	global_load_lds_dwordx4 v130, s[24:25]
	s_mov_b32 m0, s33
	s_nop 0
	global_load_lds_dwordx4 v134, s[24:25]
	s_waitcnt vmcnt(8)
	s_waitcnt lgkmcnt(0)
	s_barrier
	s_setprio 1
	s_waitcnt lgkmcnt(0)
	v_mfma_f32_16x16x32_bf16 v[126:129], v[146:149], v[184:187], v[126:129]
	v_mfma_f32_16x16x32_bf16 v[122:125], v[160:163], v[184:187], v[122:125]
	v_mfma_f32_16x16x32_bf16 v[110:113], v[146:149], v[192:195], v[110:113]
	v_mfma_f32_16x16x32_bf16 v[106:109], v[160:163], v[192:195], v[106:109]
	v_mfma_f32_16x16x32_bf16 v[94:97], v[146:149], v[200:203], v[94:97]
	v_mfma_f32_16x16x32_bf16 v[90:93], v[160:163], v[200:203], v[90:93]
	v_mfma_f32_16x16x32_bf16 v[78:81], v[146:149], v[208:211], v[78:81]
	v_mfma_f32_16x16x32_bf16 v[74:77], v[160:163], v[208:211], v[74:77]
	v_mfma_f32_16x16x32_bf16 v[126:129], v[156:159], v[188:191], v[126:129]
	v_mfma_f32_16x16x32_bf16 v[122:125], v[164:167], v[188:191], v[122:125]
	v_mfma_f32_16x16x32_bf16 v[110:113], v[156:159], v[196:199], v[110:113]
	v_mfma_f32_16x16x32_bf16 v[106:109], v[164:167], v[196:199], v[106:109]
	v_mfma_f32_16x16x32_bf16 v[94:97], v[156:159], v[204:207], v[94:97]
	v_mfma_f32_16x16x32_bf16 v[90:93], v[164:167], v[204:207], v[90:93]
	v_mfma_f32_16x16x32_bf16 v[78:81], v[156:159], v[212:215], v[78:81]
	v_mfma_f32_16x16x32_bf16 v[74:77], v[164:167], v[212:215], v[74:77]
	s_setprio 0
	s_setprio 1
	v_mfma_f32_16x16x32_bf16 v[118:121], v[168:171], v[184:187], v[118:121]
	v_mfma_f32_16x16x32_bf16 v[114:117], v[176:179], v[184:187], v[114:117]
	v_mfma_f32_16x16x32_bf16 v[102:105], v[168:171], v[192:195], v[102:105]
	v_mfma_f32_16x16x32_bf16 v[98:101], v[176:179], v[192:195], v[98:101]
	v_mfma_f32_16x16x32_bf16 v[86:89], v[168:171], v[200:203], v[86:89]
	v_mfma_f32_16x16x32_bf16 v[82:85], v[176:179], v[200:203], v[82:85]
	v_mfma_f32_16x16x32_bf16 v[70:73], v[168:171], v[208:211], v[70:73]
	v_mfma_f32_16x16x32_bf16 v[66:69], v[176:179], v[208:211], v[66:69]
	v_mfma_f32_16x16x32_bf16 v[118:121], v[172:175], v[188:191], v[118:121]
	v_mfma_f32_16x16x32_bf16 v[114:117], v[180:183], v[188:191], v[114:117]
	v_mfma_f32_16x16x32_bf16 v[102:105], v[172:175], v[196:199], v[102:105]
	v_mfma_f32_16x16x32_bf16 v[98:101], v[180:183], v[196:199], v[98:101]
	v_mfma_f32_16x16x32_bf16 v[86:89], v[172:175], v[204:207], v[86:89]
	v_mfma_f32_16x16x32_bf16 v[82:85], v[180:183], v[204:207], v[82:85]
	v_mfma_f32_16x16x32_bf16 v[70:73], v[172:175], v[212:215], v[70:73]
	v_mfma_f32_16x16x32_bf16 v[66:69], v[180:183], v[212:215], v[66:69]
	s_setprio 0
	s_barrier
	s_add_i32 s24, s47, s29
	s_mov_b32 m0, s24
	ds_read_b128 v[184:187], v154 offset:49152
	ds_read_b128 v[188:191], v154 offset:50176
	ds_read_b128 v[192:195], v154 offset:51200
	ds_read_b128 v[196:199], v154 offset:52224
	ds_read_b128 v[200:203], v154 offset:53248
	ds_read_b128 v[204:207], v154 offset:54272
	ds_read_b128 v[208:211], v154 offset:55296
	ds_read_b128 v[212:215], v154 offset:56320
	global_load_lds_dwordx4 v132, s[98:99]
	s_add_i32 m0, s24, 0x2000
	s_add_u32 s22, s22, 0x40080
	s_addc_u32 s23, s23, 0
	s_add_i32 s24, s48, s29
	global_load_lds_dwordx4 v136, s[98:99]
	s_mov_b32 m0, s24
	s_nop 0
	global_load_lds_dwordx4 v132, s[22:23]
	s_add_i32 m0, s24, 0x2000
	s_nop 0
	global_load_lds_dwordx4 v136, s[22:23]
	s_mov_b32 m0, s35
	s_nop 0
	global_load_lds_dwordx4 v130, s[100:101]
	s_mov_b32 m0, s36
	s_nop 0
	global_load_lds_dwordx4 v134, s[100:101]
	s_waitcnt vmcnt(8)
	s_waitcnt lgkmcnt(0)
	s_barrier
	s_setprio 1
	s_waitcnt lgkmcnt(0)
	v_mfma_f32_16x16x32_bf16 v[62:65], v[146:149], v[184:187], v[62:65]
	v_mfma_f32_16x16x32_bf16 v[58:61], v[160:163], v[184:187], v[58:61]
	v_mfma_f32_16x16x32_bf16 v[46:49], v[146:149], v[192:195], v[46:49]
	v_mfma_f32_16x16x32_bf16 v[42:45], v[160:163], v[192:195], v[42:45]
	v_mfma_f32_16x16x32_bf16 v[30:33], v[146:149], v[200:203], v[30:33]
	v_mfma_f32_16x16x32_bf16 v[26:29], v[160:163], v[200:203], v[26:29]
	v_mfma_f32_16x16x32_bf16 v[14:17], v[146:149], v[208:211], v[14:17]
	v_mfma_f32_16x16x32_bf16 v[10:13], v[160:163], v[208:211], v[10:13]
	v_mfma_f32_16x16x32_bf16 v[62:65], v[156:159], v[188:191], v[62:65]
	v_mfma_f32_16x16x32_bf16 v[58:61], v[164:167], v[188:191], v[58:61]
	v_mfma_f32_16x16x32_bf16 v[46:49], v[156:159], v[196:199], v[46:49]
	v_mfma_f32_16x16x32_bf16 v[42:45], v[164:167], v[196:199], v[42:45]
	v_mfma_f32_16x16x32_bf16 v[30:33], v[156:159], v[204:207], v[30:33]
	v_mfma_f32_16x16x32_bf16 v[26:29], v[164:167], v[204:207], v[26:29]
	v_mfma_f32_16x16x32_bf16 v[14:17], v[156:159], v[212:215], v[14:17]
	v_mfma_f32_16x16x32_bf16 v[10:13], v[164:167], v[212:215], v[10:13]
	s_setprio 0
	s_setprio 1
	v_mfma_f32_16x16x32_bf16 v[54:57], v[168:171], v[184:187], v[54:57]
	v_mfma_f32_16x16x32_bf16 v[50:53], v[176:179], v[184:187], v[50:53]
	v_mfma_f32_16x16x32_bf16 v[38:41], v[168:171], v[192:195], v[38:41]
	v_mfma_f32_16x16x32_bf16 v[34:37], v[176:179], v[192:195], v[34:37]
	v_mfma_f32_16x16x32_bf16 v[22:25], v[168:171], v[200:203], v[22:25]
	v_mfma_f32_16x16x32_bf16 v[18:21], v[176:179], v[200:203], v[18:21]
	v_mfma_f32_16x16x32_bf16 v[6:9], v[168:171], v[208:211], v[6:9]
	v_mfma_f32_16x16x32_bf16 v[2:5], v[176:179], v[208:211], v[2:5]
	v_mfma_f32_16x16x32_bf16 v[54:57], v[172:175], v[188:191], v[54:57]
	v_mfma_f32_16x16x32_bf16 v[50:53], v[180:183], v[188:191], v[50:53]
	v_mfma_f32_16x16x32_bf16 v[38:41], v[172:175], v[196:199], v[38:41]
	v_mfma_f32_16x16x32_bf16 v[34:37], v[180:183], v[196:199], v[34:37]
	v_mfma_f32_16x16x32_bf16 v[22:25], v[172:175], v[204:207], v[22:25]
	v_mfma_f32_16x16x32_bf16 v[18:21], v[180:183], v[204:207], v[18:21]
	v_mfma_f32_16x16x32_bf16 v[6:9], v[172:175], v[212:215], v[6:9]
	v_mfma_f32_16x16x32_bf16 v[2:5], v[180:183], v[212:215], v[2:5]
	s_setprio 0
	s_barrier
	s_add_i32 s46, s46, 2
	s_add_u32 s20, s20, 0x100
	s_addc_u32 s21, s21, 0
	s_add_u32 s44, s44, 0x100
	s_addc_u32 s45, s45, 0
	s_cmp_gt_u32 s46, 13
	s_cbranch_scc0 .LBB0_531
	s_and_b64 vcc, exec, s[8:9]
	v_readlane_b32 s42, v245, 12
	v_readlane_b32 s43, v245, 13
	s_cbranch_vccz .LBB0_534
	s_barrier

.LBB0_556:
	ds_read_b128 v[146:149], v154
	ds_read_b128 v[158:161], v154 offset:1024
	ds_read_b128 v[162:165], v154 offset:2048
	ds_read_b128 v[166:169], v154 offset:3072
	ds_read_b128 v[170:173], v155
	ds_read_b128 v[174:177], v155 offset:1024
	ds_read_b128 v[178:181], v155 offset:2048
	ds_read_b128 v[182:185], v155 offset:3072
	s_add_u32 s26, s24, 0xfffc0080
	s_addc_u32 s27, s25, -1
	s_cmp_eq_u32 s52, 12
	s_cselect_b32 s29, s17, s27
	s_cselect_b32 s28, s48, s26
	s_cselect_b32 s27, s15, s51
	s_cselect_b32 s26, s49, s50
	s_add_i32 m0, s23, 0xc000
	ds_read_b128 v[186:189], v156
	ds_read_b128 v[190:193], v156 offset:1024
	ds_read_b128 v[194:197], v156 offset:2048
	ds_read_b128 v[198:201], v156 offset:3072
	ds_read_b128 v[202:205], v156 offset:4096
	ds_read_b128 v[206:209], v156 offset:5120
	ds_read_b128 v[210:213], v156 offset:6144
	ds_read_b128 v[214:217], v156 offset:7168
	global_load_lds_dwordx4 v138, s[24:25]
	s_add_i32 m0, s23, 0xe000
	s_nop 0
	global_load_lds_dwordx4 v140, s[24:25]
	s_waitcnt vmcnt(8)
	s_waitcnt lgkmcnt(0)
	s_barrier
	s_setprio 1
	s_waitcnt lgkmcnt(0)
	v_mfma_f32_16x16x32_bf16 v[126:129], v[146:149], v[186:189], v[126:129]
	v_mfma_f32_16x16x32_bf16 v[122:125], v[162:165], v[186:189], v[122:125]
	v_mfma_f32_16x16x32_bf16 v[110:113], v[146:149], v[194:197], v[110:113]
	v_mfma_f32_16x16x32_bf16 v[106:109], v[162:165], v[194:197], v[106:109]
	v_mfma_f32_16x16x32_bf16 v[94:97], v[146:149], v[202:205], v[94:97]
	v_mfma_f32_16x16x32_bf16 v[90:93], v[162:165], v[202:205], v[90:93]
	v_mfma_f32_16x16x32_bf16 v[78:81], v[146:149], v[210:213], v[78:81]
	v_mfma_f32_16x16x32_bf16 v[74:77], v[162:165], v[210:213], v[74:77]
	v_mfma_f32_16x16x32_bf16 v[126:129], v[158:161], v[190:193], v[126:129]
	v_mfma_f32_16x16x32_bf16 v[122:125], v[166:169], v[190:193], v[122:125]
	v_mfma_f32_16x16x32_bf16 v[110:113], v[158:161], v[198:201], v[110:113]
	v_mfma_f32_16x16x32_bf16 v[106:109], v[166:169], v[198:201], v[106:109]
	v_mfma_f32_16x16x32_bf16 v[94:97], v[158:161], v[206:209], v[94:97]
	v_mfma_f32_16x16x32_bf16 v[90:93], v[166:169], v[206:209], v[90:93]
	v_mfma_f32_16x16x32_bf16 v[78:81], v[158:161], v[214:217], v[78:81]
	v_mfma_f32_16x16x32_bf16 v[74:77], v[166:169], v[214:217], v[74:77]
	s_setprio 0
	s_setprio 1
	v_mfma_f32_16x16x32_bf16 v[118:121], v[170:173], v[186:189], v[118:121]
	v_mfma_f32_16x16x32_bf16 v[114:117], v[178:181], v[186:189], v[114:117]
	v_mfma_f32_16x16x32_bf16 v[102:105], v[170:173], v[194:197], v[102:105]
	v_mfma_f32_16x16x32_bf16 v[98:101], v[178:181], v[194:197], v[98:101]
	v_mfma_f32_16x16x32_bf16 v[86:89], v[170:173], v[202:205], v[86:89]
	v_mfma_f32_16x16x32_bf16 v[82:85], v[178:181], v[202:205], v[82:85]
	v_mfma_f32_16x16x32_bf16 v[70:73], v[170:173], v[210:213], v[70:73]
	v_mfma_f32_16x16x32_bf16 v[66:69], v[178:181], v[210:213], v[66:69]
	v_mfma_f32_16x16x32_bf16 v[118:121], v[174:177], v[190:193], v[118:121]
	v_mfma_f32_16x16x32_bf16 v[114:117], v[182:185], v[190:193], v[114:117]
	v_mfma_f32_16x16x32_bf16 v[102:105], v[174:177], v[198:201], v[102:105]
	v_mfma_f32_16x16x32_bf16 v[98:101], v[182:185], v[198:201], v[98:101]
	v_mfma_f32_16x16x32_bf16 v[86:89], v[174:177], v[206:209], v[86:89]
	v_mfma_f32_16x16x32_bf16 v[82:85], v[182:185], v[206:209], v[82:85]
	v_mfma_f32_16x16x32_bf16 v[70:73], v[174:177], v[214:217], v[70:73]
	v_mfma_f32_16x16x32_bf16 v[66:69], v[182:185], v[214:217], v[66:69]
	s_setprio 0
	s_barrier
	s_add_i32 s53, s45, s36
	s_mov_b32 m0, s53
	ds_read_b128 v[186:189], v156 offset:16384
	ds_read_b128 v[190:193], v156 offset:17408
	ds_read_b128 v[194:197], v156 offset:18432
	ds_read_b128 v[198:201], v156 offset:19456
	ds_read_b128 v[202:205], v156 offset:20480
	ds_read_b128 v[206:209], v156 offset:21504
	ds_read_b128 v[210:213], v156 offset:22528
	ds_read_b128 v[214:217], v156 offset:23552
	global_load_lds_dwordx4 v132, s[26:27]
	s_add_u32 s98, s26, 0x80
	s_addc_u32 s99, s27, 0
	s_add_i32 m0, s53, 0x2000
	s_add_u32 s54, s26, 0x40000
	s_addc_u32 s55, s27, 0
	s_add_i32 s53, s46, s36
	global_load_lds_dwordx4 v136, s[26:27]
	s_mov_b32 m0, s53
	s_nop 0
	global_load_lds_dwordx4 v132, s[54:55]
	s_add_i32 m0, s53, 0x2000
	s_nop 0
	global_load_lds_dwordx4 v136, s[54:55]
	s_mov_b32 m0, s23
	s_nop 0
	global_load_lds_dwordx4 v130, s[28:29]
	s_mov_b32 m0, s37
	s_nop 0
	global_load_lds_dwordx4 v134, s[28:29]
	s_waitcnt vmcnt(8)
	s_waitcnt lgkmcnt(0)
	s_barrier
	s_setprio 1
	s_waitcnt lgkmcnt(0)
	v_mfma_f32_16x16x32_bf16 v[62:65], v[146:149], v[186:189], v[62:65]
	v_mfma_f32_16x16x32_bf16 v[58:61], v[162:165], v[186:189], v[58:61]
	v_mfma_f32_16x16x32_bf16 v[46:49], v[146:149], v[194:197], v[46:49]
	v_mfma_f32_16x16x32_bf16 v[42:45], v[162:165], v[194:197], v[42:45]
	v_mfma_f32_16x16x32_bf16 v[30:33], v[146:149], v[202:205], v[30:33]
	v_mfma_f32_16x16x32_bf16 v[26:29], v[162:165], v[202:205], v[26:29]
	v_mfma_f32_16x16x32_bf16 v[14:17], v[146:149], v[210:213], v[14:17]
	v_mfma_f32_16x16x32_bf16 v[10:13], v[162:165], v[210:213], v[10:13]
	v_mfma_f32_16x16x32_bf16 v[62:65], v[158:161], v[190:193], v[62:65]
	v_mfma_f32_16x16x32_bf16 v[58:61], v[166:169], v[190:193], v[58:61]
	v_mfma_f32_16x16x32_bf16 v[46:49], v[158:161], v[198:201], v[46:49]
	v_mfma_f32_16x16x32_bf16 v[42:45], v[166:169], v[198:201], v[42:45]
	v_mfma_f32_16x16x32_bf16 v[30:33], v[158:161], v[206:209], v[30:33]
	v_mfma_f32_16x16x32_bf16 v[26:29], v[166:169], v[206:209], v[26:29]
	v_mfma_f32_16x16x32_bf16 v[14:17], v[158:161], v[214:217], v[14:17]
	v_mfma_f32_16x16x32_bf16 v[10:13], v[166:169], v[214:217], v[10:13]
	s_setprio 0
	s_setprio 1
	v_mfma_f32_16x16x32_bf16 v[54:57], v[170:173], v[186:189], v[54:57]
	v_mfma_f32_16x16x32_bf16 v[50:53], v[178:181], v[186:189], v[50:53]
	v_mfma_f32_16x16x32_bf16 v[38:41], v[170:173], v[194:197], v[38:41]
	v_mfma_f32_16x16x32_bf16 v[34:37], v[178:181], v[194:197], v[34:37]
	v_mfma_f32_16x16x32_bf16 v[22:25], v[170:173], v[202:205], v[22:25]
	v_mfma_f32_16x16x32_bf16 v[18:21], v[178:181], v[202:205], v[18:21]
	v_mfma_f32_16x16x32_bf16 v[6:9], v[170:173], v[210:213], v[6:9]
	v_mfma_f32_16x16x32_bf16 v[2:5], v[178:181], v[210:213], v[2:5]
	v_mfma_f32_16x16x32_bf16 v[54:57], v[174:177], v[190:193], v[54:57]
	v_mfma_f32_16x16x32_bf16 v[50:53], v[182:185], v[190:193], v[50:53]
	v_mfma_f32_16x16x32_bf16 v[38:41], v[174:177], v[198:201], v[38:41]
	v_mfma_f32_16x16x32_bf16 v[34:37], v[182:185], v[198:201], v[34:37]
	v_mfma_f32_16x16x32_bf16 v[22:25], v[174:177], v[206:209], v[22:25]
	v_mfma_f32_16x16x32_bf16 v[18:21], v[182:185], v[206:209], v[18:21]
	v_mfma_f32_16x16x32_bf16 v[6:9], v[174:177], v[214:217], v[6:9]
	v_mfma_f32_16x16x32_bf16 v[2:5], v[182:185], v[214:217], v[2:5]
	s_setprio 0
	s_barrier
	s_add_u32 s100, s28, 0x80
	s_addc_u32 s101, s29, 0
	s_add_i32 s53, 0, 0x18000
	v_add_u32_e32 v157, s53, v152
	s_add_i32 s54, 0, 0x1c000
	ds_read_b128 v[146:149], v157
	ds_read_b128 v[158:161], v157 offset:1024
	ds_read_b128 v[162:165], v157 offset:2048
	ds_read_b128 v[166:169], v157 offset:3072
	v_add_u32_e32 v157, s54, v152
	ds_read_b128 v[170:173], v157
	ds_read_b128 v[174:177], v157 offset:1024
	ds_read_b128 v[178:181], v157 offset:2048
	ds_read_b128 v[182:185], v157 offset:3072
	s_add_u32 s28, s28, 0x40000
	s_addc_u32 s29, s29, 0
	s_mov_b32 m0, s38
	ds_read_b128 v[186:189], v156 offset:32768
	ds_read_b128 v[190:193], v156 offset:33792
	ds_read_b128 v[194:197], v156 offset:34816
	ds_read_b128 v[198:201], v156 offset:35840
	ds_read_b128 v[202:205], v156 offset:36864
	ds_read_b128 v[206:209], v156 offset:37888
	ds_read_b128 v[210:213], v156 offset:38912
	ds_read_b128 v[214:217], v156 offset:39936
	global_load_lds_dwordx4 v130, s[28:29]
	s_mov_b32 m0, s39
	s_nop 0
	global_load_lds_dwordx4 v134, s[28:29]
	s_waitcnt vmcnt(8)
	s_waitcnt lgkmcnt(0)
	s_barrier
	s_setprio 1
	s_waitcnt lgkmcnt(0)
	v_mfma_f32_16x16x32_bf16 v[126:129], v[146:149], v[186:189], v[126:129]
	v_mfma_f32_16x16x32_bf16 v[122:125], v[162:165], v[186:189], v[122:125]
	v_mfma_f32_16x16x32_bf16 v[110:113], v[146:149], v[194:197], v[110:113]
	v_mfma_f32_16x16x32_bf16 v[106:109], v[162:165], v[194:197], v[106:109]
	v_mfma_f32_16x16x32_bf16 v[94:97], v[146:149], v[202:205], v[94:97]
	v_mfma_f32_16x16x32_bf16 v[90:93], v[162:165], v[202:205], v[90:93]
	v_mfma_f32_16x16x32_bf16 v[78:81], v[146:149], v[210:213], v[78:81]
	v_mfma_f32_16x16x32_bf16 v[74:77], v[162:165], v[210:213], v[74:77]
	v_mfma_f32_16x16x32_bf16 v[126:129], v[158:161], v[190:193], v[126:129]
	v_mfma_f32_16x16x32_bf16 v[122:125], v[166:169], v[190:193], v[122:125]
	v_mfma_f32_16x16x32_bf16 v[110:113], v[158:161], v[198:201], v[110:113]
	v_mfma_f32_16x16x32_bf16 v[106:109], v[166:169], v[198:201], v[106:109]
	v_mfma_f32_16x16x32_bf16 v[94:97], v[158:161], v[206:209], v[94:97]
	v_mfma_f32_16x16x32_bf16 v[90:93], v[166:169], v[206:209], v[90:93]
	v_mfma_f32_16x16x32_bf16 v[78:81], v[158:161], v[214:217], v[78:81]
	v_mfma_f32_16x16x32_bf16 v[74:77], v[166:169], v[214:217], v[74:77]
	s_setprio 0
	s_setprio 1
	v_mfma_f32_16x16x32_bf16 v[118:121], v[170:173], v[186:189], v[118:121]
	v_mfma_f32_16x16x32_bf16 v[114:117], v[178:181], v[186:189], v[114:117]
	v_mfma_f32_16x16x32_bf16 v[102:105], v[170:173], v[194:197], v[102:105]
	v_mfma_f32_16x16x32_bf16 v[98:101], v[178:181], v[194:197], v[98:101]
	v_mfma_f32_16x16x32_bf16 v[86:89], v[170:173], v[202:205], v[86:89]
	v_mfma_f32_16x16x32_bf16 v[82:85], v[178:181], v[202:205], v[82:85]
	v_mfma_f32_16x16x32_bf16 v[70:73], v[170:173], v[210:213], v[70:73]
	v_mfma_f32_16x16x32_bf16 v[66:69], v[178:181], v[210:213], v[66:69]
	v_mfma_f32_16x16x32_bf16 v[118:121], v[174:177], v[190:193], v[118:121]
	v_mfma_f32_16x16x32_bf16 v[114:117], v[182:185], v[190:193], v[114:117]
	v_mfma_f32_16x16x32_bf16 v[102:105], v[174:177], v[198:201], v[102:105]
	v_mfma_f32_16x16x32_bf16 v[98:101], v[182:185], v[198:201], v[98:101]
	v_mfma_f32_16x16x32_bf16 v[86:89], v[174:177], v[206:209], v[86:89]
	v_mfma_f32_16x16x32_bf16 v[82:85], v[182:185], v[206:209], v[82:85]
	v_mfma_f32_16x16x32_bf16 v[70:73], v[174:177], v[214:217], v[70:73]
	v_mfma_f32_16x16x32_bf16 v[66:69], v[182:185], v[214:217], v[66:69]
	s_setprio 0
	s_barrier
	s_add_i32 s28, s53, s36
	s_mov_b32 m0, s28
	ds_read_b128 v[186:189], v156 offset:49152
	ds_read_b128 v[190:193], v156 offset:50176
	ds_read_b128 v[194:197], v156 offset:51200
	ds_read_b128 v[198:201], v156 offset:52224
	ds_read_b128 v[202:205], v156 offset:53248
	ds_read_b128 v[206:209], v156 offset:54272
	ds_read_b128 v[210:213], v156 offset:55296
	ds_read_b128 v[214:217], v156 offset:56320
	global_load_lds_dwordx4 v132, s[98:99]
	s_add_i32 m0, s28, 0x2000
	s_add_u32 s26, s26, 0x40080
	s_addc_u32 s27, s27, 0
	s_add_i32 s28, s54, s36
	global_load_lds_dwordx4 v136, s[98:99]
	s_mov_b32 m0, s28
	s_nop 0
	global_load_lds_dwordx4 v132, s[26:27]
	s_add_i32 m0, s28, 0x2000
	s_nop 0
	global_load_lds_dwordx4 v136, s[26:27]
	s_mov_b32 m0, s41
	s_nop 0
	global_load_lds_dwordx4 v130, s[100:101]
	s_mov_b32 m0, s42
	s_nop 0
	global_load_lds_dwordx4 v134, s[100:101]
	s_waitcnt vmcnt(8)
	s_waitcnt lgkmcnt(0)
	s_barrier
	s_setprio 1
	s_waitcnt lgkmcnt(0)
	v_mfma_f32_16x16x32_bf16 v[62:65], v[146:149], v[186:189], v[62:65]
	v_mfma_f32_16x16x32_bf16 v[58:61], v[162:165], v[186:189], v[58:61]
	v_mfma_f32_16x16x32_bf16 v[46:49], v[146:149], v[194:197], v[46:49]
	v_mfma_f32_16x16x32_bf16 v[42:45], v[162:165], v[194:197], v[42:45]
	v_mfma_f32_16x16x32_bf16 v[30:33], v[146:149], v[202:205], v[30:33]
	v_mfma_f32_16x16x32_bf16 v[26:29], v[162:165], v[202:205], v[26:29]
	v_mfma_f32_16x16x32_bf16 v[14:17], v[146:149], v[210:213], v[14:17]
	v_mfma_f32_16x16x32_bf16 v[10:13], v[162:165], v[210:213], v[10:13]
	v_mfma_f32_16x16x32_bf16 v[62:65], v[158:161], v[190:193], v[62:65]
	v_mfma_f32_16x16x32_bf16 v[58:61], v[166:169], v[190:193], v[58:61]
	v_mfma_f32_16x16x32_bf16 v[46:49], v[158:161], v[198:201], v[46:49]
	v_mfma_f32_16x16x32_bf16 v[42:45], v[166:169], v[198:201], v[42:45]
	v_mfma_f32_16x16x32_bf16 v[30:33], v[158:161], v[206:209], v[30:33]
	v_mfma_f32_16x16x32_bf16 v[26:29], v[166:169], v[206:209], v[26:29]
	v_mfma_f32_16x16x32_bf16 v[14:17], v[158:161], v[214:217], v[14:17]
	v_mfma_f32_16x16x32_bf16 v[10:13], v[166:169], v[214:217], v[10:13]
	s_setprio 0
	s_setprio 1
	v_mfma_f32_16x16x32_bf16 v[54:57], v[170:173], v[186:189], v[54:57]
	v_mfma_f32_16x16x32_bf16 v[50:53], v[178:181], v[186:189], v[50:53]
	v_mfma_f32_16x16x32_bf16 v[38:41], v[170:173], v[194:197], v[38:41]
	v_mfma_f32_16x16x32_bf16 v[34:37], v[178:181], v[194:197], v[34:37]
	v_mfma_f32_16x16x32_bf16 v[22:25], v[170:173], v[202:205], v[22:25]
	v_mfma_f32_16x16x32_bf16 v[18:21], v[178:181], v[202:205], v[18:21]
	v_mfma_f32_16x16x32_bf16 v[6:9], v[170:173], v[210:213], v[6:9]
	v_mfma_f32_16x16x32_bf16 v[2:5], v[178:181], v[210:213], v[2:5]
	v_mfma_f32_16x16x32_bf16 v[54:57], v[174:177], v[190:193], v[54:57]
	v_mfma_f32_16x16x32_bf16 v[50:53], v[182:185], v[190:193], v[50:53]
	v_mfma_f32_16x16x32_bf16 v[38:41], v[174:177], v[198:201], v[38:41]
	v_mfma_f32_16x16x32_bf16 v[34:37], v[182:185], v[198:201], v[34:37]
	v_mfma_f32_16x16x32_bf16 v[22:25], v[174:177], v[206:209], v[22:25]
	v_mfma_f32_16x16x32_bf16 v[18:21], v[182:185], v[206:209], v[18:21]
	v_mfma_f32_16x16x32_bf16 v[6:9], v[174:177], v[214:217], v[6:9]
	v_mfma_f32_16x16x32_bf16 v[2:5], v[182:185], v[214:217], v[2:5]
	s_setprio 0
	s_barrier
	s_add_i32 s52, s52, 2
	s_add_u32 s24, s24, 0x100
	s_addc_u32 s25, s25, 0
	s_add_u32 s50, s50, 0x100
	s_addc_u32 s51, s51, 0
	s_cmp_gt_u32 s52, 13
	s_cbranch_scc0 .LBB0_556
	s_and_b64 vcc, exec, s[10:11]
	s_cbranch_vccz .LBB0_559
	s_barrier

.LBB0_635:
	ds_read_b128 v[152:155], v148
	ds_read_b128 v[156:159], v148 offset:1024
	ds_read_b128 v[160:163], v148 offset:2048
	ds_read_b128 v[164:167], v148 offset:3072
	ds_read_b128 v[168:171], v149
	ds_read_b128 v[172:175], v149 offset:1024
	ds_read_b128 v[176:179], v149 offset:2048
	ds_read_b128 v[180:183], v149 offset:3072
	s_add_u32 s34, s30, 0xfff80080
	s_addc_u32 s35, s31, -1
	s_cmp_eq_u32 s60, 28
	s_cselect_b32 s37, s25, s35
	s_cselect_b32 s36, s56, s34
	s_cselect_b32 s35, s23, s59
	s_cselect_b32 s34, s57, s58
	s_add_i32 m0, s21, 0xc000
	ds_read_b128 v[184:187], v150
	ds_read_b128 v[188:191], v150 offset:1024
	ds_read_b128 v[192:195], v150 offset:2048
	ds_read_b128 v[196:199], v150 offset:3072
	ds_read_b128 v[200:203], v150 offset:4096
	ds_read_b128 v[204:207], v150 offset:5120
	ds_read_b128 v[208:211], v150 offset:6144
	ds_read_b128 v[212:215], v150 offset:7168
	global_load_lds_dwordx4 v138, s[30:31]
	s_add_i32 m0, s21, 0xe000
	s_nop 0
	global_load_lds_dwordx4 v140, s[30:31]
	s_waitcnt vmcnt(8)
	s_waitcnt lgkmcnt(0)
	s_barrier
	s_setprio 1
	s_waitcnt lgkmcnt(0)
	v_mfma_f32_16x16x32_bf16 v[126:129], v[152:155], v[184:187], v[126:129]
	v_mfma_f32_16x16x32_bf16 v[122:125], v[160:163], v[184:187], v[122:125]
	v_mfma_f32_16x16x32_bf16 v[118:121], v[152:155], v[192:195], v[118:121]
	v_mfma_f32_16x16x32_bf16 v[114:117], v[160:163], v[192:195], v[114:117]
	v_mfma_f32_16x16x32_bf16 v[102:105], v[152:155], v[200:203], v[102:105]
	v_mfma_f32_16x16x32_bf16 v[98:101], v[160:163], v[200:203], v[98:101]
	v_mfma_f32_16x16x32_bf16 v[86:89], v[152:155], v[208:211], v[86:89]
	v_mfma_f32_16x16x32_bf16 v[82:85], v[160:163], v[208:211], v[82:85]
	v_mfma_f32_16x16x32_bf16 v[126:129], v[156:159], v[188:191], v[126:129]
	v_mfma_f32_16x16x32_bf16 v[122:125], v[164:167], v[188:191], v[122:125]
	v_mfma_f32_16x16x32_bf16 v[118:121], v[156:159], v[196:199], v[118:121]
	v_mfma_f32_16x16x32_bf16 v[114:117], v[164:167], v[196:199], v[114:117]
	v_mfma_f32_16x16x32_bf16 v[102:105], v[156:159], v[204:207], v[102:105]
	v_mfma_f32_16x16x32_bf16 v[98:101], v[164:167], v[204:207], v[98:101]
	v_mfma_f32_16x16x32_bf16 v[86:89], v[156:159], v[212:215], v[86:89]
	v_mfma_f32_16x16x32_bf16 v[82:85], v[164:167], v[212:215], v[82:85]
	s_setprio 0
	s_setprio 1
	v_mfma_f32_16x16x32_bf16 v[110:113], v[168:171], v[184:187], v[110:113]
	v_mfma_f32_16x16x32_bf16 v[106:109], v[176:179], v[184:187], v[106:109]
	v_mfma_f32_16x16x32_bf16 v[94:97], v[168:171], v[192:195], v[94:97]
	v_mfma_f32_16x16x32_bf16 v[90:93], v[176:179], v[192:195], v[90:93]
	v_mfma_f32_16x16x32_bf16 v[78:81], v[168:171], v[200:203], v[78:81]
	v_mfma_f32_16x16x32_bf16 v[74:77], v[176:179], v[200:203], v[74:77]
	v_mfma_f32_16x16x32_bf16 v[70:73], v[168:171], v[208:211], v[70:73]
	v_mfma_f32_16x16x32_bf16 v[66:69], v[176:179], v[208:211], v[66:69]
	v_mfma_f32_16x16x32_bf16 v[110:113], v[172:175], v[188:191], v[110:113]
	v_mfma_f32_16x16x32_bf16 v[106:109], v[180:183], v[188:191], v[106:109]
	v_mfma_f32_16x16x32_bf16 v[94:97], v[172:175], v[196:199], v[94:97]
	v_mfma_f32_16x16x32_bf16 v[90:93], v[180:183], v[196:199], v[90:93]
	v_mfma_f32_16x16x32_bf16 v[78:81], v[172:175], v[204:207], v[78:81]
	v_mfma_f32_16x16x32_bf16 v[74:77], v[180:183], v[204:207], v[74:77]
	v_mfma_f32_16x16x32_bf16 v[70:73], v[172:175], v[212:215], v[70:73]
	v_mfma_f32_16x16x32_bf16 v[66:69], v[180:183], v[212:215], v[66:69]
	s_setprio 0
	s_barrier
	s_add_i32 s61, s49, s40
	s_mov_b32 m0, s61
	ds_read_b128 v[184:187], v150 offset:16384
	ds_read_b128 v[188:191], v150 offset:17408
	ds_read_b128 v[192:195], v150 offset:18432
	ds_read_b128 v[196:199], v150 offset:19456
	ds_read_b128 v[200:203], v150 offset:20480
	ds_read_b128 v[204:207], v150 offset:21504
	ds_read_b128 v[208:211], v150 offset:22528
	ds_read_b128 v[212:215], v150 offset:23552
	global_load_lds_dwordx4 v132, s[34:35]
	s_add_u32 s98, s34, 0x80
	s_addc_u32 s99, s35, 0
	s_add_i32 m0, s61, 0x2000
	s_add_u32 s62, s34, 0x80000
	s_addc_u32 s63, s35, 0
	s_add_i32 s61, s50, s40
	global_load_lds_dwordx4 v136, s[34:35]
	s_mov_b32 m0, s61
	s_nop 0
	global_load_lds_dwordx4 v132, s[62:63]
	s_add_i32 m0, s61, 0x2000
	s_nop 0
	global_load_lds_dwordx4 v136, s[62:63]
	s_mov_b32 m0, s21
	s_nop 0
	global_load_lds_dwordx4 v130, s[36:37]
	s_mov_b32 m0, s41
	s_nop 0
	global_load_lds_dwordx4 v134, s[36:37]
	s_waitcnt vmcnt(8)
	s_waitcnt lgkmcnt(0)
	s_barrier
	s_setprio 1
	s_waitcnt lgkmcnt(0)
	v_mfma_f32_16x16x32_bf16 v[62:65], v[152:155], v[184:187], v[62:65]
	v_mfma_f32_16x16x32_bf16 v[58:61], v[160:163], v[184:187], v[58:61]
	v_mfma_f32_16x16x32_bf16 v[54:57], v[152:155], v[192:195], v[54:57]
	v_mfma_f32_16x16x32_bf16 v[50:53], v[160:163], v[192:195], v[50:53]
	v_mfma_f32_16x16x32_bf16 v[38:41], v[152:155], v[200:203], v[38:41]
	v_mfma_f32_16x16x32_bf16 v[34:37], v[160:163], v[200:203], v[34:37]
	v_mfma_f32_16x16x32_bf16 v[22:25], v[152:155], v[208:211], v[22:25]
	v_mfma_f32_16x16x32_bf16 v[18:21], v[160:163], v[208:211], v[18:21]
	v_mfma_f32_16x16x32_bf16 v[62:65], v[156:159], v[188:191], v[62:65]
	v_mfma_f32_16x16x32_bf16 v[58:61], v[164:167], v[188:191], v[58:61]
	v_mfma_f32_16x16x32_bf16 v[54:57], v[156:159], v[196:199], v[54:57]
	v_mfma_f32_16x16x32_bf16 v[50:53], v[164:167], v[196:199], v[50:53]
	v_mfma_f32_16x16x32_bf16 v[38:41], v[156:159], v[204:207], v[38:41]
	v_mfma_f32_16x16x32_bf16 v[34:37], v[164:167], v[204:207], v[34:37]
	v_mfma_f32_16x16x32_bf16 v[22:25], v[156:159], v[212:215], v[22:25]
	v_mfma_f32_16x16x32_bf16 v[18:21], v[164:167], v[212:215], v[18:21]
	s_setprio 0
	s_setprio 1
	v_mfma_f32_16x16x32_bf16 v[46:49], v[168:171], v[184:187], v[46:49]
	v_mfma_f32_16x16x32_bf16 v[42:45], v[176:179], v[184:187], v[42:45]
	v_mfma_f32_16x16x32_bf16 v[30:33], v[168:171], v[192:195], v[30:33]
	v_mfma_f32_16x16x32_bf16 v[26:29], v[176:179], v[192:195], v[26:29]
	v_mfma_f32_16x16x32_bf16 v[14:17], v[168:171], v[200:203], v[14:17]
	v_mfma_f32_16x16x32_bf16 v[10:13], v[176:179], v[200:203], v[10:13]
	v_mfma_f32_16x16x32_bf16 v[6:9], v[168:171], v[208:211], v[6:9]
	v_mfma_f32_16x16x32_bf16 v[2:5], v[176:179], v[208:211], v[2:5]
	v_mfma_f32_16x16x32_bf16 v[46:49], v[172:175], v[188:191], v[46:49]
	v_mfma_f32_16x16x32_bf16 v[42:45], v[180:183], v[188:191], v[42:45]
	v_mfma_f32_16x16x32_bf16 v[30:33], v[172:175], v[196:199], v[30:33]
	v_mfma_f32_16x16x32_bf16 v[26:29], v[180:183], v[196:199], v[26:29]
	v_mfma_f32_16x16x32_bf16 v[14:17], v[172:175], v[204:207], v[14:17]
	v_mfma_f32_16x16x32_bf16 v[10:13], v[180:183], v[204:207], v[10:13]
	v_mfma_f32_16x16x32_bf16 v[6:9], v[172:175], v[212:215], v[6:9]
	v_mfma_f32_16x16x32_bf16 v[2:5], v[180:183], v[212:215], v[2:5]
	s_setprio 0
	s_barrier
	s_add_u32 s100, s36, 0x80
	s_addc_u32 s101, s37, 0
	s_add_i32 s61, 0, 0x18000
	v_add_u32_e32 v151, s61, v146
	s_add_i32 s62, 0, 0x1c000
	ds_read_b128 v[152:155], v151
	ds_read_b128 v[156:159], v151 offset:1024
	ds_read_b128 v[160:163], v151 offset:2048
	ds_read_b128 v[164:167], v151 offset:3072
	v_add_u32_e32 v151, s62, v146
	ds_read_b128 v[168:171], v151
	ds_read_b128 v[172:175], v151 offset:1024
	ds_read_b128 v[176:179], v151 offset:2048
	ds_read_b128 v[180:183], v151 offset:3072
	s_add_u32 s36, s36, 0x80000
	s_addc_u32 s37, s37, 0
	s_mov_b32 m0, s42
	ds_read_b128 v[184:187], v150 offset:32768
	ds_read_b128 v[188:191], v150 offset:33792
	ds_read_b128 v[192:195], v150 offset:34816
	ds_read_b128 v[196:199], v150 offset:35840
	ds_read_b128 v[200:203], v150 offset:36864
	ds_read_b128 v[204:207], v150 offset:37888
	ds_read_b128 v[208:211], v150 offset:38912
	ds_read_b128 v[212:215], v150 offset:39936
	global_load_lds_dwordx4 v130, s[36:37]
	s_mov_b32 m0, s43
	s_nop 0
	global_load_lds_dwordx4 v134, s[36:37]
	s_waitcnt vmcnt(8)
	s_waitcnt lgkmcnt(0)
	s_barrier
	s_setprio 1
	s_waitcnt lgkmcnt(0)
	v_mfma_f32_16x16x32_bf16 v[126:129], v[152:155], v[184:187], v[126:129]
	v_mfma_f32_16x16x32_bf16 v[122:125], v[160:163], v[184:187], v[122:125]
	v_mfma_f32_16x16x32_bf16 v[118:121], v[152:155], v[192:195], v[118:121]
	v_mfma_f32_16x16x32_bf16 v[114:117], v[160:163], v[192:195], v[114:117]
	v_mfma_f32_16x16x32_bf16 v[102:105], v[152:155], v[200:203], v[102:105]
	v_mfma_f32_16x16x32_bf16 v[98:101], v[160:163], v[200:203], v[98:101]
	v_mfma_f32_16x16x32_bf16 v[86:89], v[152:155], v[208:211], v[86:89]
	v_mfma_f32_16x16x32_bf16 v[82:85], v[160:163], v[208:211], v[82:85]
	v_mfma_f32_16x16x32_bf16 v[126:129], v[156:159], v[188:191], v[126:129]
	v_mfma_f32_16x16x32_bf16 v[122:125], v[164:167], v[188:191], v[122:125]
	v_mfma_f32_16x16x32_bf16 v[118:121], v[156:159], v[196:199], v[118:121]
	v_mfma_f32_16x16x32_bf16 v[114:117], v[164:167], v[196:199], v[114:117]
	v_mfma_f32_16x16x32_bf16 v[102:105], v[156:159], v[204:207], v[102:105]
	v_mfma_f32_16x16x32_bf16 v[98:101], v[164:167], v[204:207], v[98:101]
	v_mfma_f32_16x16x32_bf16 v[86:89], v[156:159], v[212:215], v[86:89]
	v_mfma_f32_16x16x32_bf16 v[82:85], v[164:167], v[212:215], v[82:85]
	s_setprio 0
	s_setprio 1
	v_mfma_f32_16x16x32_bf16 v[110:113], v[168:171], v[184:187], v[110:113]
	v_mfma_f32_16x16x32_bf16 v[106:109], v[176:179], v[184:187], v[106:109]
	v_mfma_f32_16x16x32_bf16 v[94:97], v[168:171], v[192:195], v[94:97]
	v_mfma_f32_16x16x32_bf16 v[90:93], v[176:179], v[192:195], v[90:93]
	v_mfma_f32_16x16x32_bf16 v[78:81], v[168:171], v[200:203], v[78:81]
	v_mfma_f32_16x16x32_bf16 v[74:77], v[176:179], v[200:203], v[74:77]
	v_mfma_f32_16x16x32_bf16 v[70:73], v[168:171], v[208:211], v[70:73]
	v_mfma_f32_16x16x32_bf16 v[66:69], v[176:179], v[208:211], v[66:69]
	v_mfma_f32_16x16x32_bf16 v[110:113], v[172:175], v[188:191], v[110:113]
	v_mfma_f32_16x16x32_bf16 v[106:109], v[180:183], v[188:191], v[106:109]
	v_mfma_f32_16x16x32_bf16 v[94:97], v[172:175], v[196:199], v[94:97]
	v_mfma_f32_16x16x32_bf16 v[90:93], v[180:183], v[196:199], v[90:93]
	v_mfma_f32_16x16x32_bf16 v[78:81], v[172:175], v[204:207], v[78:81]
	v_mfma_f32_16x16x32_bf16 v[74:77], v[180:183], v[204:207], v[74:77]
	v_mfma_f32_16x16x32_bf16 v[70:73], v[172:175], v[212:215], v[70:73]
	v_mfma_f32_16x16x32_bf16 v[66:69], v[180:183], v[212:215], v[66:69]
	s_setprio 0
	s_barrier
	s_add_i32 s36, s61, s40
	s_mov_b32 m0, s36
	ds_read_b128 v[184:187], v150 offset:49152
	ds_read_b128 v[188:191], v150 offset:50176
	ds_read_b128 v[192:195], v150 offset:51200
	ds_read_b128 v[196:199], v150 offset:52224
	ds_read_b128 v[200:203], v150 offset:53248
	ds_read_b128 v[204:207], v150 offset:54272
	ds_read_b128 v[208:211], v150 offset:55296
	ds_read_b128 v[212:215], v150 offset:56320
	global_load_lds_dwordx4 v132, s[98:99]
	s_add_i32 m0, s36, 0x2000
	s_add_u32 s34, s34, 0x80080
	s_addc_u32 s35, s35, 0
	s_add_i32 s36, s62, s40
	global_load_lds_dwordx4 v136, s[98:99]
	s_mov_b32 m0, s36
	s_nop 0
	global_load_lds_dwordx4 v132, s[34:35]
	s_add_i32 m0, s36, 0x2000
	s_nop 0
	global_load_lds_dwordx4 v136, s[34:35]
	s_mov_b32 m0, s45
	s_nop 0
	global_load_lds_dwordx4 v130, s[100:101]
	s_mov_b32 m0, s46
	s_nop 0
	global_load_lds_dwordx4 v134, s[100:101]
	s_waitcnt vmcnt(8)
	s_waitcnt lgkmcnt(0)
	s_barrier
	s_setprio 1
	s_waitcnt lgkmcnt(0)
	v_mfma_f32_16x16x32_bf16 v[62:65], v[152:155], v[184:187], v[62:65]
	v_mfma_f32_16x16x32_bf16 v[58:61], v[160:163], v[184:187], v[58:61]
	v_mfma_f32_16x16x32_bf16 v[54:57], v[152:155], v[192:195], v[54:57]
	v_mfma_f32_16x16x32_bf16 v[50:53], v[160:163], v[192:195], v[50:53]
	v_mfma_f32_16x16x32_bf16 v[38:41], v[152:155], v[200:203], v[38:41]
	v_mfma_f32_16x16x32_bf16 v[34:37], v[160:163], v[200:203], v[34:37]
	v_mfma_f32_16x16x32_bf16 v[22:25], v[152:155], v[208:211], v[22:25]
	v_mfma_f32_16x16x32_bf16 v[18:21], v[160:163], v[208:211], v[18:21]
	v_mfma_f32_16x16x32_bf16 v[62:65], v[156:159], v[188:191], v[62:65]
	v_mfma_f32_16x16x32_bf16 v[58:61], v[164:167], v[188:191], v[58:61]
	v_mfma_f32_16x16x32_bf16 v[54:57], v[156:159], v[196:199], v[54:57]
	v_mfma_f32_16x16x32_bf16 v[50:53], v[164:167], v[196:199], v[50:53]
	v_mfma_f32_16x16x32_bf16 v[38:41], v[156:159], v[204:207], v[38:41]
	v_mfma_f32_16x16x32_bf16 v[34:37], v[164:167], v[204:207], v[34:37]
	v_mfma_f32_16x16x32_bf16 v[22:25], v[156:159], v[212:215], v[22:25]
	v_mfma_f32_16x16x32_bf16 v[18:21], v[164:167], v[212:215], v[18:21]
	s_setprio 0
	s_setprio 1
	v_mfma_f32_16x16x32_bf16 v[46:49], v[168:171], v[184:187], v[46:49]
	v_mfma_f32_16x16x32_bf16 v[42:45], v[176:179], v[184:187], v[42:45]
	v_mfma_f32_16x16x32_bf16 v[30:33], v[168:171], v[192:195], v[30:33]
	v_mfma_f32_16x16x32_bf16 v[26:29], v[176:179], v[192:195], v[26:29]
	v_mfma_f32_16x16x32_bf16 v[14:17], v[168:171], v[200:203], v[14:17]
	v_mfma_f32_16x16x32_bf16 v[10:13], v[176:179], v[200:203], v[10:13]
	v_mfma_f32_16x16x32_bf16 v[6:9], v[168:171], v[208:211], v[6:9]
	v_mfma_f32_16x16x32_bf16 v[2:5], v[176:179], v[208:211], v[2:5]
	v_mfma_f32_16x16x32_bf16 v[46:49], v[172:175], v[188:191], v[46:49]
	v_mfma_f32_16x16x32_bf16 v[42:45], v[180:183], v[188:191], v[42:45]
	v_mfma_f32_16x16x32_bf16 v[30:33], v[172:175], v[196:199], v[30:33]
	v_mfma_f32_16x16x32_bf16 v[26:29], v[180:183], v[196:199], v[26:29]
	v_mfma_f32_16x16x32_bf16 v[14:17], v[172:175], v[204:207], v[14:17]
	v_mfma_f32_16x16x32_bf16 v[10:13], v[180:183], v[204:207], v[10:13]
	v_mfma_f32_16x16x32_bf16 v[6:9], v[172:175], v[212:215], v[6:9]
	v_mfma_f32_16x16x32_bf16 v[2:5], v[180:183], v[212:215], v[2:5]
	s_setprio 0
	s_barrier
	s_add_i32 s60, s60, 2
	s_add_u32 s30, s30, 0x100
	s_addc_u32 s31, s31, 0
	s_add_u32 s58, s58, 0x100
	s_addc_u32 s59, s59, 0
	s_cmp_gt_u32 s60, 29
	s_cbranch_scc0 .LBB0_635
	s_and_b64 vcc, exec, s[12:13]
	s_cbranch_vccz .LBB0_638
	s_barrier

.LBB0_770:
	ds_read_b128 v[146:149], v156
	ds_read_b128 v[150:153], v156 offset:1024
	ds_read_b128 v[160:163], v156 offset:2048
	ds_read_b128 v[164:167], v156 offset:3072
	ds_read_b128 v[168:171], v157
	ds_read_b128 v[172:175], v157 offset:1024
	ds_read_b128 v[176:179], v157 offset:2048
	ds_read_b128 v[180:183], v157 offset:3072
	s_add_u32 s26, s24, 0xfff80080
	s_addc_u32 s27, s25, -1
	s_cmp_eq_u32 s52, 28
	s_cselect_b32 s29, s17, s27
	s_cselect_b32 s28, s48, s26
	s_cselect_b32 s27, s15, s51
	s_cselect_b32 s26, s49, s50
	s_add_i32 m0, s23, 0xc000
	ds_read_b128 v[184:187], v158
	ds_read_b128 v[188:191], v158 offset:1024
	ds_read_b128 v[192:195], v158 offset:2048
	ds_read_b128 v[196:199], v158 offset:3072
	ds_read_b128 v[200:203], v158 offset:4096
	ds_read_b128 v[204:207], v158 offset:5120
	ds_read_b128 v[208:211], v158 offset:6144
	ds_read_b128 v[212:215], v158 offset:7168
	global_load_lds_dwordx4 v138, s[24:25]
	s_add_i32 m0, s23, 0xe000
	s_nop 0
	global_load_lds_dwordx4 v140, s[24:25]
	s_waitcnt vmcnt(8)
	s_waitcnt lgkmcnt(0)
	s_barrier
	s_setprio 1
	s_waitcnt lgkmcnt(0)
	v_mfma_f32_16x16x32_bf16 v[126:129], v[146:149], v[184:187], v[126:129]
	v_mfma_f32_16x16x32_bf16 v[122:125], v[160:163], v[184:187], v[122:125]
	v_mfma_f32_16x16x32_bf16 v[110:113], v[146:149], v[192:195], v[110:113]
	v_mfma_f32_16x16x32_bf16 v[106:109], v[160:163], v[192:195], v[106:109]
	v_mfma_f32_16x16x32_bf16 v[94:97], v[146:149], v[200:203], v[94:97]
	v_mfma_f32_16x16x32_bf16 v[90:93], v[160:163], v[200:203], v[90:93]
	v_mfma_f32_16x16x32_bf16 v[78:81], v[146:149], v[208:211], v[78:81]
	v_mfma_f32_16x16x32_bf16 v[74:77], v[160:163], v[208:211], v[74:77]
	v_mfma_f32_16x16x32_bf16 v[126:129], v[150:153], v[188:191], v[126:129]
	v_mfma_f32_16x16x32_bf16 v[122:125], v[164:167], v[188:191], v[122:125]
	v_mfma_f32_16x16x32_bf16 v[110:113], v[150:153], v[196:199], v[110:113]
	v_mfma_f32_16x16x32_bf16 v[106:109], v[164:167], v[196:199], v[106:109]
	v_mfma_f32_16x16x32_bf16 v[94:97], v[150:153], v[204:207], v[94:97]
	v_mfma_f32_16x16x32_bf16 v[90:93], v[164:167], v[204:207], v[90:93]
	v_mfma_f32_16x16x32_bf16 v[78:81], v[150:153], v[212:215], v[78:81]
	v_mfma_f32_16x16x32_bf16 v[74:77], v[164:167], v[212:215], v[74:77]
	s_setprio 0
	s_setprio 1
	v_mfma_f32_16x16x32_bf16 v[118:121], v[168:171], v[184:187], v[118:121]
	v_mfma_f32_16x16x32_bf16 v[114:117], v[176:179], v[184:187], v[114:117]
	v_mfma_f32_16x16x32_bf16 v[102:105], v[168:171], v[192:195], v[102:105]
	v_mfma_f32_16x16x32_bf16 v[98:101], v[176:179], v[192:195], v[98:101]
	v_mfma_f32_16x16x32_bf16 v[86:89], v[168:171], v[200:203], v[86:89]
	v_mfma_f32_16x16x32_bf16 v[82:85], v[176:179], v[200:203], v[82:85]
	v_mfma_f32_16x16x32_bf16 v[70:73], v[168:171], v[208:211], v[70:73]
	v_mfma_f32_16x16x32_bf16 v[66:69], v[176:179], v[208:211], v[66:69]
	v_mfma_f32_16x16x32_bf16 v[118:121], v[172:175], v[188:191], v[118:121]
	v_mfma_f32_16x16x32_bf16 v[114:117], v[180:183], v[188:191], v[114:117]
	v_mfma_f32_16x16x32_bf16 v[102:105], v[172:175], v[196:199], v[102:105]
	v_mfma_f32_16x16x32_bf16 v[98:101], v[180:183], v[196:199], v[98:101]
	v_mfma_f32_16x16x32_bf16 v[86:89], v[172:175], v[204:207], v[86:89]
	v_mfma_f32_16x16x32_bf16 v[82:85], v[180:183], v[204:207], v[82:85]
	v_mfma_f32_16x16x32_bf16 v[70:73], v[172:175], v[212:215], v[70:73]
	v_mfma_f32_16x16x32_bf16 v[66:69], v[180:183], v[212:215], v[66:69]
	s_setprio 0
	s_barrier
	s_add_i32 s53, s44, s33
	s_mov_b32 m0, s53
	ds_read_b128 v[184:187], v158 offset:16384
	ds_read_b128 v[188:191], v158 offset:17408
	ds_read_b128 v[192:195], v158 offset:18432
	ds_read_b128 v[196:199], v158 offset:19456
	ds_read_b128 v[200:203], v158 offset:20480
	ds_read_b128 v[204:207], v158 offset:21504
	ds_read_b128 v[208:211], v158 offset:22528
	ds_read_b128 v[212:215], v158 offset:23552
	global_load_lds_dwordx4 v134, s[26:27]
	s_add_u32 s98, s26, 0x80
	s_addc_u32 s99, s27, 0
	s_add_i32 m0, s53, 0x2000
	s_add_u32 s54, s26, 0x80000
	s_addc_u32 s55, s27, 0
	s_add_i32 s53, s45, s33
	global_load_lds_dwordx4 v130, s[26:27]
	s_mov_b32 m0, s53
	s_nop 0
	global_load_lds_dwordx4 v134, s[54:55]
	s_add_i32 m0, s53, 0x2000
	s_nop 0
	global_load_lds_dwordx4 v130, s[54:55]
	s_mov_b32 m0, s23
	s_nop 0
	global_load_lds_dwordx4 v136, s[28:29]
	s_mov_b32 m0, s36
	s_nop 0
	global_load_lds_dwordx4 v132, s[28:29]
	s_waitcnt vmcnt(8)
	s_waitcnt lgkmcnt(0)
	s_barrier
	s_setprio 1
	s_waitcnt lgkmcnt(0)
	v_mfma_f32_16x16x32_bf16 v[62:65], v[146:149], v[184:187], v[62:65]
	v_mfma_f32_16x16x32_bf16 v[58:61], v[160:163], v[184:187], v[58:61]
	v_mfma_f32_16x16x32_bf16 v[46:49], v[146:149], v[192:195], v[46:49]
	v_mfma_f32_16x16x32_bf16 v[42:45], v[160:163], v[192:195], v[42:45]
	v_mfma_f32_16x16x32_bf16 v[30:33], v[146:149], v[200:203], v[30:33]
	v_mfma_f32_16x16x32_bf16 v[26:29], v[160:163], v[200:203], v[26:29]
	v_mfma_f32_16x16x32_bf16 v[14:17], v[146:149], v[208:211], v[14:17]
	v_mfma_f32_16x16x32_bf16 v[10:13], v[160:163], v[208:211], v[10:13]
	v_mfma_f32_16x16x32_bf16 v[62:65], v[150:153], v[188:191], v[62:65]
	v_mfma_f32_16x16x32_bf16 v[58:61], v[164:167], v[188:191], v[58:61]
	v_mfma_f32_16x16x32_bf16 v[46:49], v[150:153], v[196:199], v[46:49]
	v_mfma_f32_16x16x32_bf16 v[42:45], v[164:167], v[196:199], v[42:45]
	v_mfma_f32_16x16x32_bf16 v[30:33], v[150:153], v[204:207], v[30:33]
	v_mfma_f32_16x16x32_bf16 v[26:29], v[164:167], v[204:207], v[26:29]
	v_mfma_f32_16x16x32_bf16 v[14:17], v[150:153], v[212:215], v[14:17]
	v_mfma_f32_16x16x32_bf16 v[10:13], v[164:167], v[212:215], v[10:13]
	s_setprio 0
	s_setprio 1
	v_mfma_f32_16x16x32_bf16 v[54:57], v[168:171], v[184:187], v[54:57]
	v_mfma_f32_16x16x32_bf16 v[50:53], v[176:179], v[184:187], v[50:53]
	v_mfma_f32_16x16x32_bf16 v[38:41], v[168:171], v[192:195], v[38:41]
	v_mfma_f32_16x16x32_bf16 v[34:37], v[176:179], v[192:195], v[34:37]
	v_mfma_f32_16x16x32_bf16 v[22:25], v[168:171], v[200:203], v[22:25]
	v_mfma_f32_16x16x32_bf16 v[18:21], v[176:179], v[200:203], v[18:21]
	v_mfma_f32_16x16x32_bf16 v[6:9], v[168:171], v[208:211], v[6:9]
	v_mfma_f32_16x16x32_bf16 v[2:5], v[176:179], v[208:211], v[2:5]
	v_mfma_f32_16x16x32_bf16 v[54:57], v[172:175], v[188:191], v[54:57]
	v_mfma_f32_16x16x32_bf16 v[50:53], v[180:183], v[188:191], v[50:53]
	v_mfma_f32_16x16x32_bf16 v[38:41], v[172:175], v[196:199], v[38:41]
	v_mfma_f32_16x16x32_bf16 v[34:37], v[180:183], v[196:199], v[34:37]
	v_mfma_f32_16x16x32_bf16 v[22:25], v[172:175], v[204:207], v[22:25]
	v_mfma_f32_16x16x32_bf16 v[18:21], v[180:183], v[204:207], v[18:21]
	v_mfma_f32_16x16x32_bf16 v[6:9], v[172:175], v[212:215], v[6:9]
	v_mfma_f32_16x16x32_bf16 v[2:5], v[180:183], v[212:215], v[2:5]
	s_setprio 0
	s_barrier
	s_add_u32 s100, s28, 0x80
	s_addc_u32 s101, s29, 0
	s_add_i32 s53, 0, 0x18000
	v_add_u32_e32 v159, s53, v154
	s_add_i32 s54, 0, 0x1c000
	ds_read_b128 v[146:149], v159
	ds_read_b128 v[150:153], v159 offset:1024
	ds_read_b128 v[160:163], v159 offset:2048
	ds_read_b128 v[164:167], v159 offset:3072
	v_add_u32_e32 v159, s54, v154
	ds_read_b128 v[168:171], v159
	ds_read_b128 v[172:175], v159 offset:1024
	ds_read_b128 v[176:179], v159 offset:2048
	ds_read_b128 v[180:183], v159 offset:3072
	s_add_u32 s28, s28, 0x80000
	s_addc_u32 s29, s29, 0
	s_mov_b32 m0, s37
	ds_read_b128 v[184:187], v158 offset:32768
	ds_read_b128 v[188:191], v158 offset:33792
	ds_read_b128 v[192:195], v158 offset:34816
	ds_read_b128 v[196:199], v158 offset:35840
	ds_read_b128 v[200:203], v158 offset:36864
	ds_read_b128 v[204:207], v158 offset:37888
	ds_read_b128 v[208:211], v158 offset:38912
	ds_read_b128 v[212:215], v158 offset:39936
	global_load_lds_dwordx4 v136, s[28:29]
	s_mov_b32 m0, s38
	s_nop 0
	global_load_lds_dwordx4 v132, s[28:29]
	s_waitcnt vmcnt(8)
	s_waitcnt lgkmcnt(0)
	s_barrier
	s_setprio 1
	s_waitcnt lgkmcnt(0)
	v_mfma_f32_16x16x32_bf16 v[126:129], v[146:149], v[184:187], v[126:129]
	v_mfma_f32_16x16x32_bf16 v[122:125], v[160:163], v[184:187], v[122:125]
	v_mfma_f32_16x16x32_bf16 v[110:113], v[146:149], v[192:195], v[110:113]
	v_mfma_f32_16x16x32_bf16 v[106:109], v[160:163], v[192:195], v[106:109]
	v_mfma_f32_16x16x32_bf16 v[94:97], v[146:149], v[200:203], v[94:97]
	v_mfma_f32_16x16x32_bf16 v[90:93], v[160:163], v[200:203], v[90:93]
	v_mfma_f32_16x16x32_bf16 v[78:81], v[146:149], v[208:211], v[78:81]
	v_mfma_f32_16x16x32_bf16 v[74:77], v[160:163], v[208:211], v[74:77]
	v_mfma_f32_16x16x32_bf16 v[126:129], v[150:153], v[188:191], v[126:129]
	v_mfma_f32_16x16x32_bf16 v[122:125], v[164:167], v[188:191], v[122:125]
	v_mfma_f32_16x16x32_bf16 v[110:113], v[150:153], v[196:199], v[110:113]
	v_mfma_f32_16x16x32_bf16 v[106:109], v[164:167], v[196:199], v[106:109]
	v_mfma_f32_16x16x32_bf16 v[94:97], v[150:153], v[204:207], v[94:97]
	v_mfma_f32_16x16x32_bf16 v[90:93], v[164:167], v[204:207], v[90:93]
	v_mfma_f32_16x16x32_bf16 v[78:81], v[150:153], v[212:215], v[78:81]
	v_mfma_f32_16x16x32_bf16 v[74:77], v[164:167], v[212:215], v[74:77]
	s_setprio 0
	s_setprio 1
	v_mfma_f32_16x16x32_bf16 v[118:121], v[168:171], v[184:187], v[118:121]
	v_mfma_f32_16x16x32_bf16 v[114:117], v[176:179], v[184:187], v[114:117]
	v_mfma_f32_16x16x32_bf16 v[102:105], v[168:171], v[192:195], v[102:105]
	v_mfma_f32_16x16x32_bf16 v[98:101], v[176:179], v[192:195], v[98:101]
	v_mfma_f32_16x16x32_bf16 v[86:89], v[168:171], v[200:203], v[86:89]
	v_mfma_f32_16x16x32_bf16 v[82:85], v[176:179], v[200:203], v[82:85]
	v_mfma_f32_16x16x32_bf16 v[70:73], v[168:171], v[208:211], v[70:73]
	v_mfma_f32_16x16x32_bf16 v[66:69], v[176:179], v[208:211], v[66:69]
	v_mfma_f32_16x16x32_bf16 v[118:121], v[172:175], v[188:191], v[118:121]
	v_mfma_f32_16x16x32_bf16 v[114:117], v[180:183], v[188:191], v[114:117]
	v_mfma_f32_16x16x32_bf16 v[102:105], v[172:175], v[196:199], v[102:105]
	v_mfma_f32_16x16x32_bf16 v[98:101], v[180:183], v[196:199], v[98:101]
	v_mfma_f32_16x16x32_bf16 v[86:89], v[172:175], v[204:207], v[86:89]
	v_mfma_f32_16x16x32_bf16 v[82:85], v[180:183], v[204:207], v[82:85]
	v_mfma_f32_16x16x32_bf16 v[70:73], v[172:175], v[212:215], v[70:73]
	v_mfma_f32_16x16x32_bf16 v[66:69], v[180:183], v[212:215], v[66:69]
	s_setprio 0
	s_barrier
	s_add_i32 s28, s53, s33
	s_mov_b32 m0, s28
	ds_read_b128 v[184:187], v158 offset:49152
	ds_read_b128 v[188:191], v158 offset:50176
	ds_read_b128 v[192:195], v158 offset:51200
	ds_read_b128 v[196:199], v158 offset:52224
	ds_read_b128 v[200:203], v158 offset:53248
	ds_read_b128 v[204:207], v158 offset:54272
	ds_read_b128 v[208:211], v158 offset:55296
	ds_read_b128 v[212:215], v158 offset:56320
	global_load_lds_dwordx4 v134, s[98:99]
	s_add_i32 m0, s28, 0x2000
	s_add_u32 s26, s26, 0x80080
	s_addc_u32 s27, s27, 0
	s_add_i32 s28, s54, s33
	global_load_lds_dwordx4 v130, s[98:99]
	s_mov_b32 m0, s28
	s_nop 0
	global_load_lds_dwordx4 v134, s[26:27]
	s_add_i32 m0, s28, 0x2000
	s_nop 0
	global_load_lds_dwordx4 v130, s[26:27]
	s_mov_b32 m0, s40
	s_nop 0
	global_load_lds_dwordx4 v136, s[100:101]
	s_mov_b32 m0, s41
	s_nop 0
	global_load_lds_dwordx4 v132, s[100:101]
	s_waitcnt vmcnt(8)
	s_waitcnt lgkmcnt(0)
	s_barrier
	s_setprio 1
	s_waitcnt lgkmcnt(0)
	v_mfma_f32_16x16x32_bf16 v[62:65], v[146:149], v[184:187], v[62:65]
	v_mfma_f32_16x16x32_bf16 v[58:61], v[160:163], v[184:187], v[58:61]
	v_mfma_f32_16x16x32_bf16 v[46:49], v[146:149], v[192:195], v[46:49]
	v_mfma_f32_16x16x32_bf16 v[42:45], v[160:163], v[192:195], v[42:45]
	v_mfma_f32_16x16x32_bf16 v[30:33], v[146:149], v[200:203], v[30:33]
	v_mfma_f32_16x16x32_bf16 v[26:29], v[160:163], v[200:203], v[26:29]
	v_mfma_f32_16x16x32_bf16 v[14:17], v[146:149], v[208:211], v[14:17]
	v_mfma_f32_16x16x32_bf16 v[10:13], v[160:163], v[208:211], v[10:13]
	v_mfma_f32_16x16x32_bf16 v[62:65], v[150:153], v[188:191], v[62:65]
	v_mfma_f32_16x16x32_bf16 v[58:61], v[164:167], v[188:191], v[58:61]
	v_mfma_f32_16x16x32_bf16 v[46:49], v[150:153], v[196:199], v[46:49]
	v_mfma_f32_16x16x32_bf16 v[42:45], v[164:167], v[196:199], v[42:45]
	v_mfma_f32_16x16x32_bf16 v[30:33], v[150:153], v[204:207], v[30:33]
	v_mfma_f32_16x16x32_bf16 v[26:29], v[164:167], v[204:207], v[26:29]
	v_mfma_f32_16x16x32_bf16 v[14:17], v[150:153], v[212:215], v[14:17]
	v_mfma_f32_16x16x32_bf16 v[10:13], v[164:167], v[212:215], v[10:13]
	s_setprio 0
	s_setprio 1
	v_mfma_f32_16x16x32_bf16 v[54:57], v[168:171], v[184:187], v[54:57]
	v_mfma_f32_16x16x32_bf16 v[50:53], v[176:179], v[184:187], v[50:53]
	v_mfma_f32_16x16x32_bf16 v[38:41], v[168:171], v[192:195], v[38:41]
	v_mfma_f32_16x16x32_bf16 v[34:37], v[176:179], v[192:195], v[34:37]
	v_mfma_f32_16x16x32_bf16 v[22:25], v[168:171], v[200:203], v[22:25]
	v_mfma_f32_16x16x32_bf16 v[18:21], v[176:179], v[200:203], v[18:21]
	v_mfma_f32_16x16x32_bf16 v[6:9], v[168:171], v[208:211], v[6:9]
	v_mfma_f32_16x16x32_bf16 v[2:5], v[176:179], v[208:211], v[2:5]
	v_mfma_f32_16x16x32_bf16 v[54:57], v[172:175], v[188:191], v[54:57]
	v_mfma_f32_16x16x32_bf16 v[50:53], v[180:183], v[188:191], v[50:53]
	v_mfma_f32_16x16x32_bf16 v[38:41], v[172:175], v[196:199], v[38:41]
	v_mfma_f32_16x16x32_bf16 v[34:37], v[180:183], v[196:199], v[34:37]
	v_mfma_f32_16x16x32_bf16 v[22:25], v[172:175], v[204:207], v[22:25]
	v_mfma_f32_16x16x32_bf16 v[18:21], v[180:183], v[204:207], v[18:21]
	v_mfma_f32_16x16x32_bf16 v[6:9], v[172:175], v[212:215], v[6:9]
	v_mfma_f32_16x16x32_bf16 v[2:5], v[180:183], v[212:215], v[2:5]
	s_setprio 0
	s_barrier
	s_add_i32 s52, s52, 2
	s_add_u32 s24, s24, 0x100
	s_addc_u32 s25, s25, 0
	s_add_u32 s50, s50, 0x100
	s_addc_u32 s51, s51, 0
	s_cmp_gt_u32 s52, 29
	s_cbranch_scc0 .LBB0_770
	s_and_b64 vcc, exec, s[12:13]
	s_cbranch_vccz .LBB0_773
	s_barrier

.LBB0_853:
	ds_read_b128 v[150:153], v147
	ds_read_b128 v[154:157], v147 offset:1024
	ds_read_b128 v[158:161], v147 offset:2048
	ds_read_b128 v[162:165], v147 offset:3072
	ds_read_b128 v[166:169], v148
	ds_read_b128 v[170:173], v148 offset:1024
	ds_read_b128 v[174:177], v148 offset:2048
	ds_read_b128 v[178:181], v148 offset:3072
	s_add_u32 s24, s22, 0xffea0080
	s_addc_u32 s25, s23, -1
	s_cmpk_eq_i32 s56, 0x54
	s_cselect_b32 s27, s1, s25
	s_cselect_b32 s26, s0, s24
	s_cselect_b32 s25, s21, s55
	s_cselect_b32 s24, s20, s54
	s_add_i32 m0, s35, 0xc000
	ds_read_b128 v[182:185], v149
	ds_read_b128 v[186:189], v149 offset:1024
	ds_read_b128 v[190:193], v149 offset:2048
	ds_read_b128 v[194:197], v149 offset:3072
	ds_read_b128 v[198:201], v149 offset:4096
	ds_read_b128 v[202:205], v149 offset:5120
	ds_read_b128 v[206:209], v149 offset:6144
	ds_read_b128 v[210:213], v149 offset:7168
	global_load_lds_dwordx4 v136, s[22:23]
	s_add_i32 m0, s35, 0xe000
	s_nop 0
	global_load_lds_dwordx4 v138, s[22:23]
	s_waitcnt vmcnt(8)
	s_waitcnt lgkmcnt(0)
	s_barrier
	s_setprio 1
	s_waitcnt lgkmcnt(0)
	v_mfma_f32_16x16x32_bf16 v[124:127], v[150:153], v[182:185], v[124:127]
	v_mfma_f32_16x16x32_bf16 v[120:123], v[158:161], v[182:185], v[120:123]
	v_mfma_f32_16x16x32_bf16 v[116:119], v[150:153], v[190:193], v[116:119]
	v_mfma_f32_16x16x32_bf16 v[112:115], v[158:161], v[190:193], v[112:115]
	v_mfma_f32_16x16x32_bf16 v[100:103], v[150:153], v[198:201], v[100:103]
	v_mfma_f32_16x16x32_bf16 v[96:99], v[158:161], v[198:201], v[96:99]
	v_mfma_f32_16x16x32_bf16 v[84:87], v[150:153], v[206:209], v[84:87]
	v_mfma_f32_16x16x32_bf16 v[80:83], v[158:161], v[206:209], v[80:83]
	v_mfma_f32_16x16x32_bf16 v[124:127], v[154:157], v[186:189], v[124:127]
	v_mfma_f32_16x16x32_bf16 v[120:123], v[162:165], v[186:189], v[120:123]
	v_mfma_f32_16x16x32_bf16 v[116:119], v[154:157], v[194:197], v[116:119]
	v_mfma_f32_16x16x32_bf16 v[112:115], v[162:165], v[194:197], v[112:115]
	v_mfma_f32_16x16x32_bf16 v[100:103], v[154:157], v[202:205], v[100:103]
	v_mfma_f32_16x16x32_bf16 v[96:99], v[162:165], v[202:205], v[96:99]
	v_mfma_f32_16x16x32_bf16 v[84:87], v[154:157], v[210:213], v[84:87]
	v_mfma_f32_16x16x32_bf16 v[80:83], v[162:165], v[210:213], v[80:83]
	s_setprio 0
	s_setprio 1
	v_mfma_f32_16x16x32_bf16 v[108:111], v[166:169], v[182:185], v[108:111]
	v_mfma_f32_16x16x32_bf16 v[104:107], v[174:177], v[182:185], v[104:107]
	v_mfma_f32_16x16x32_bf16 v[92:95], v[166:169], v[190:193], v[92:95]
	v_mfma_f32_16x16x32_bf16 v[88:91], v[174:177], v[190:193], v[88:91]
	v_mfma_f32_16x16x32_bf16 v[76:79], v[166:169], v[198:201], v[76:79]
	v_mfma_f32_16x16x32_bf16 v[72:75], v[174:177], v[198:201], v[72:75]
	v_mfma_f32_16x16x32_bf16 v[68:71], v[166:169], v[206:209], v[68:71]
	v_mfma_f32_16x16x32_bf16 v[64:67], v[174:177], v[206:209], v[64:67]
	v_mfma_f32_16x16x32_bf16 v[108:111], v[170:173], v[186:189], v[108:111]
	v_mfma_f32_16x16x32_bf16 v[104:107], v[178:181], v[186:189], v[104:107]
	v_mfma_f32_16x16x32_bf16 v[92:95], v[170:173], v[194:197], v[92:95]
	v_mfma_f32_16x16x32_bf16 v[88:91], v[178:181], v[194:197], v[88:91]
	v_mfma_f32_16x16x32_bf16 v[76:79], v[170:173], v[202:205], v[76:79]
	v_mfma_f32_16x16x32_bf16 v[72:75], v[178:181], v[202:205], v[72:75]
	v_mfma_f32_16x16x32_bf16 v[68:71], v[170:173], v[210:213], v[68:71]
	v_mfma_f32_16x16x32_bf16 v[64:67], v[178:181], v[210:213], v[64:67]
	s_setprio 0
	s_barrier
	s_add_i32 s57, s44, s34
	s_mov_b32 m0, s57
	ds_read_b128 v[182:185], v149 offset:16384
	ds_read_b128 v[186:189], v149 offset:17408
	ds_read_b128 v[190:193], v149 offset:18432
	ds_read_b128 v[194:197], v149 offset:19456
	ds_read_b128 v[198:201], v149 offset:20480
	ds_read_b128 v[202:205], v149 offset:21504
	ds_read_b128 v[206:209], v149 offset:22528
	ds_read_b128 v[210:213], v149 offset:23552
	global_load_lds_dwordx4 v130, s[24:25]
	s_add_u32 s98, s24, 0x80
	s_addc_u32 s99, s25, 0
	s_add_i32 m0, s57, 0x2000
	s_add_u32 s58, s24, 0x160000
	s_addc_u32 s59, s25, 0
	s_add_i32 s57, s45, s34
	global_load_lds_dwordx4 v134, s[24:25]
	s_mov_b32 m0, s57
	s_nop 0
	global_load_lds_dwordx4 v130, s[58:59]
	s_add_i32 m0, s57, 0x2000
	s_nop 0
	global_load_lds_dwordx4 v134, s[58:59]
	s_mov_b32 m0, s35
	s_nop 0
	global_load_lds_dwordx4 v128, s[26:27]
	s_mov_b32 m0, s36
	s_nop 0
	global_load_lds_dwordx4 v132, s[26:27]
	s_waitcnt vmcnt(8)
	s_waitcnt lgkmcnt(0)
	s_barrier
	s_setprio 1
	s_waitcnt lgkmcnt(0)
	v_mfma_f32_16x16x32_bf16 v[60:63], v[150:153], v[182:185], v[60:63]
	v_mfma_f32_16x16x32_bf16 v[56:59], v[158:161], v[182:185], v[56:59]
	v_mfma_f32_16x16x32_bf16 v[52:55], v[150:153], v[190:193], v[52:55]
	v_mfma_f32_16x16x32_bf16 v[48:51], v[158:161], v[190:193], v[48:51]
	v_mfma_f32_16x16x32_bf16 v[36:39], v[150:153], v[198:201], v[36:39]
	v_mfma_f32_16x16x32_bf16 v[32:35], v[158:161], v[198:201], v[32:35]
	v_mfma_f32_16x16x32_bf16 v[20:23], v[150:153], v[206:209], v[20:23]
	v_mfma_f32_16x16x32_bf16 v[16:19], v[158:161], v[206:209], v[16:19]
	v_mfma_f32_16x16x32_bf16 v[60:63], v[154:157], v[186:189], v[60:63]
	v_mfma_f32_16x16x32_bf16 v[56:59], v[162:165], v[186:189], v[56:59]
	v_mfma_f32_16x16x32_bf16 v[52:55], v[154:157], v[194:197], v[52:55]
	v_mfma_f32_16x16x32_bf16 v[48:51], v[162:165], v[194:197], v[48:51]
	v_mfma_f32_16x16x32_bf16 v[36:39], v[154:157], v[202:205], v[36:39]
	v_mfma_f32_16x16x32_bf16 v[32:35], v[162:165], v[202:205], v[32:35]
	v_mfma_f32_16x16x32_bf16 v[20:23], v[154:157], v[210:213], v[20:23]
	v_mfma_f32_16x16x32_bf16 v[16:19], v[162:165], v[210:213], v[16:19]
	s_setprio 0
	s_setprio 1
	v_mfma_f32_16x16x32_bf16 v[44:47], v[166:169], v[182:185], v[44:47]
	v_mfma_f32_16x16x32_bf16 v[40:43], v[174:177], v[182:185], v[40:43]
	v_mfma_f32_16x16x32_bf16 v[28:31], v[166:169], v[190:193], v[28:31]
	v_mfma_f32_16x16x32_bf16 v[24:27], v[174:177], v[190:193], v[24:27]
	v_mfma_f32_16x16x32_bf16 v[12:15], v[166:169], v[198:201], v[12:15]
	v_mfma_f32_16x16x32_bf16 v[8:11], v[174:177], v[198:201], v[8:11]
	v_mfma_f32_16x16x32_bf16 v[4:7], v[166:169], v[206:209], v[4:7]
	v_mfma_f32_16x16x32_bf16 v[0:3], v[174:177], v[206:209], v[0:3]
	v_mfma_f32_16x16x32_bf16 v[44:47], v[170:173], v[186:189], v[44:47]
	v_mfma_f32_16x16x32_bf16 v[40:43], v[178:181], v[186:189], v[40:43]
	v_mfma_f32_16x16x32_bf16 v[28:31], v[170:173], v[194:197], v[28:31]
	v_mfma_f32_16x16x32_bf16 v[24:27], v[178:181], v[194:197], v[24:27]
	v_mfma_f32_16x16x32_bf16 v[12:15], v[170:173], v[202:205], v[12:15]
	v_mfma_f32_16x16x32_bf16 v[8:11], v[178:181], v[202:205], v[8:11]
	v_mfma_f32_16x16x32_bf16 v[4:7], v[170:173], v[210:213], v[4:7]
	v_mfma_f32_16x16x32_bf16 v[0:3], v[178:181], v[210:213], v[0:3]
	s_setprio 0
	s_barrier
	s_add_u32 s100, s26, 0x80
	s_addc_u32 s101, s27, 0
	s_add_i32 s57, 0, 0x18000
	s_add_i32 s58, 0, 0x1c000
	v_add_u32_e32 v162, s57, v145
	v_add_u32_e32 v178, s58, v145
	ds_read_b128 v[150:153], v162
	ds_read_b128 v[154:157], v162 offset:1024
	ds_read_b128 v[158:161], v162 offset:2048
	ds_read_b128 v[162:165], v162 offset:3072
	ds_read_b128 v[166:169], v178
	ds_read_b128 v[170:173], v178 offset:1024
	ds_read_b128 v[174:177], v178 offset:2048
	ds_read_b128 v[178:181], v178 offset:3072
	s_add_u32 s26, s26, 0x160000
	s_addc_u32 s27, s27, 0
	s_mov_b32 m0, s37
	ds_read_b128 v[182:185], v149 offset:32768
	ds_read_b128 v[186:189], v149 offset:33792
	ds_read_b128 v[190:193], v149 offset:34816
	ds_read_b128 v[194:197], v149 offset:35840
	ds_read_b128 v[198:201], v149 offset:36864
	ds_read_b128 v[202:205], v149 offset:37888
	ds_read_b128 v[206:209], v149 offset:38912
	ds_read_b128 v[210:213], v149 offset:39936
	global_load_lds_dwordx4 v128, s[26:27]
	s_mov_b32 m0, s38
	s_nop 0
	global_load_lds_dwordx4 v132, s[26:27]
	s_waitcnt vmcnt(8)
	s_waitcnt lgkmcnt(0)
	s_barrier
	s_setprio 1
	s_waitcnt lgkmcnt(0)
	v_mfma_f32_16x16x32_bf16 v[124:127], v[150:153], v[182:185], v[124:127]
	v_mfma_f32_16x16x32_bf16 v[120:123], v[158:161], v[182:185], v[120:123]
	v_mfma_f32_16x16x32_bf16 v[116:119], v[150:153], v[190:193], v[116:119]
	v_mfma_f32_16x16x32_bf16 v[112:115], v[158:161], v[190:193], v[112:115]
	v_mfma_f32_16x16x32_bf16 v[100:103], v[150:153], v[198:201], v[100:103]
	v_mfma_f32_16x16x32_bf16 v[96:99], v[158:161], v[198:201], v[96:99]
	v_mfma_f32_16x16x32_bf16 v[84:87], v[150:153], v[206:209], v[84:87]
	v_mfma_f32_16x16x32_bf16 v[80:83], v[158:161], v[206:209], v[80:83]
	v_mfma_f32_16x16x32_bf16 v[124:127], v[154:157], v[186:189], v[124:127]
	v_mfma_f32_16x16x32_bf16 v[120:123], v[162:165], v[186:189], v[120:123]
	v_mfma_f32_16x16x32_bf16 v[116:119], v[154:157], v[194:197], v[116:119]
	v_mfma_f32_16x16x32_bf16 v[112:115], v[162:165], v[194:197], v[112:115]
	v_mfma_f32_16x16x32_bf16 v[100:103], v[154:157], v[202:205], v[100:103]
	v_mfma_f32_16x16x32_bf16 v[96:99], v[162:165], v[202:205], v[96:99]
	v_mfma_f32_16x16x32_bf16 v[84:87], v[154:157], v[210:213], v[84:87]
	v_mfma_f32_16x16x32_bf16 v[80:83], v[162:165], v[210:213], v[80:83]
	s_setprio 0
	s_setprio 1
	v_mfma_f32_16x16x32_bf16 v[108:111], v[166:169], v[182:185], v[108:111]
	v_mfma_f32_16x16x32_bf16 v[104:107], v[174:177], v[182:185], v[104:107]
	v_mfma_f32_16x16x32_bf16 v[92:95], v[166:169], v[190:193], v[92:95]
	v_mfma_f32_16x16x32_bf16 v[88:91], v[174:177], v[190:193], v[88:91]
	v_mfma_f32_16x16x32_bf16 v[76:79], v[166:169], v[198:201], v[76:79]
	v_mfma_f32_16x16x32_bf16 v[72:75], v[174:177], v[198:201], v[72:75]
	v_mfma_f32_16x16x32_bf16 v[68:71], v[166:169], v[206:209], v[68:71]
	v_mfma_f32_16x16x32_bf16 v[64:67], v[174:177], v[206:209], v[64:67]
	v_mfma_f32_16x16x32_bf16 v[108:111], v[170:173], v[186:189], v[108:111]
	v_mfma_f32_16x16x32_bf16 v[104:107], v[178:181], v[186:189], v[104:107]
	v_mfma_f32_16x16x32_bf16 v[92:95], v[170:173], v[194:197], v[92:95]
	v_mfma_f32_16x16x32_bf16 v[88:91], v[178:181], v[194:197], v[88:91]
	v_mfma_f32_16x16x32_bf16 v[76:79], v[170:173], v[202:205], v[76:79]
	v_mfma_f32_16x16x32_bf16 v[72:75], v[178:181], v[202:205], v[72:75]
	v_mfma_f32_16x16x32_bf16 v[68:71], v[170:173], v[210:213], v[68:71]
	v_mfma_f32_16x16x32_bf16 v[64:67], v[178:181], v[210:213], v[64:67]
	s_setprio 0
	s_barrier
	s_add_i32 s26, s57, s34
	s_mov_b32 m0, s26
	ds_read_b128 v[182:185], v149 offset:49152
	ds_read_b128 v[186:189], v149 offset:50176
	ds_read_b128 v[190:193], v149 offset:51200
	ds_read_b128 v[194:197], v149 offset:52224
	ds_read_b128 v[198:201], v149 offset:53248
	ds_read_b128 v[202:205], v149 offset:54272
	ds_read_b128 v[206:209], v149 offset:55296
	ds_read_b128 v[210:213], v149 offset:56320
	global_load_lds_dwordx4 v130, s[98:99]
	s_add_i32 m0, s26, 0x2000
	s_add_u32 s24, s24, 0x160080
	s_addc_u32 s25, s25, 0
	s_add_i32 s26, s58, s34
	global_load_lds_dwordx4 v134, s[98:99]
	s_mov_b32 m0, s26
	s_nop 0
	global_load_lds_dwordx4 v130, s[24:25]
	s_add_i32 m0, s26, 0x2000
	s_nop 0
	global_load_lds_dwordx4 v134, s[24:25]
	s_mov_b32 m0, s40
	s_nop 0
	global_load_lds_dwordx4 v128, s[100:101]
	s_mov_b32 m0, s41
	s_nop 0
	global_load_lds_dwordx4 v132, s[100:101]
	s_waitcnt vmcnt(8)
	s_waitcnt lgkmcnt(0)
	s_barrier
	s_setprio 1
	s_waitcnt lgkmcnt(0)
	v_mfma_f32_16x16x32_bf16 v[60:63], v[150:153], v[182:185], v[60:63]
	v_mfma_f32_16x16x32_bf16 v[56:59], v[158:161], v[182:185], v[56:59]
	v_mfma_f32_16x16x32_bf16 v[52:55], v[150:153], v[190:193], v[52:55]
	v_mfma_f32_16x16x32_bf16 v[48:51], v[158:161], v[190:193], v[48:51]
	v_mfma_f32_16x16x32_bf16 v[36:39], v[150:153], v[198:201], v[36:39]
	v_mfma_f32_16x16x32_bf16 v[32:35], v[158:161], v[198:201], v[32:35]
	v_mfma_f32_16x16x32_bf16 v[20:23], v[150:153], v[206:209], v[20:23]
	v_mfma_f32_16x16x32_bf16 v[16:19], v[158:161], v[206:209], v[16:19]
	v_mfma_f32_16x16x32_bf16 v[60:63], v[154:157], v[186:189], v[60:63]
	v_mfma_f32_16x16x32_bf16 v[56:59], v[162:165], v[186:189], v[56:59]
	v_mfma_f32_16x16x32_bf16 v[52:55], v[154:157], v[194:197], v[52:55]
	v_mfma_f32_16x16x32_bf16 v[48:51], v[162:165], v[194:197], v[48:51]
	v_mfma_f32_16x16x32_bf16 v[36:39], v[154:157], v[202:205], v[36:39]
	v_mfma_f32_16x16x32_bf16 v[32:35], v[162:165], v[202:205], v[32:35]
	v_mfma_f32_16x16x32_bf16 v[20:23], v[154:157], v[210:213], v[20:23]
	v_mfma_f32_16x16x32_bf16 v[16:19], v[162:165], v[210:213], v[16:19]
	s_setprio 0
	s_setprio 1
	v_mfma_f32_16x16x32_bf16 v[44:47], v[166:169], v[182:185], v[44:47]
	v_mfma_f32_16x16x32_bf16 v[40:43], v[174:177], v[182:185], v[40:43]
	v_mfma_f32_16x16x32_bf16 v[28:31], v[166:169], v[190:193], v[28:31]
	v_mfma_f32_16x16x32_bf16 v[24:27], v[174:177], v[190:193], v[24:27]
	v_mfma_f32_16x16x32_bf16 v[12:15], v[166:169], v[198:201], v[12:15]
	v_mfma_f32_16x16x32_bf16 v[8:11], v[174:177], v[198:201], v[8:11]
	v_mfma_f32_16x16x32_bf16 v[4:7], v[166:169], v[206:209], v[4:7]
	v_mfma_f32_16x16x32_bf16 v[0:3], v[174:177], v[206:209], v[0:3]
	v_mfma_f32_16x16x32_bf16 v[44:47], v[170:173], v[186:189], v[44:47]
	v_mfma_f32_16x16x32_bf16 v[40:43], v[178:181], v[186:189], v[40:43]
	v_mfma_f32_16x16x32_bf16 v[28:31], v[170:173], v[194:197], v[28:31]
	v_mfma_f32_16x16x32_bf16 v[24:27], v[178:181], v[194:197], v[24:27]
	v_mfma_f32_16x16x32_bf16 v[12:15], v[170:173], v[202:205], v[12:15]
	v_mfma_f32_16x16x32_bf16 v[8:11], v[178:181], v[202:205], v[8:11]
	v_mfma_f32_16x16x32_bf16 v[4:7], v[170:173], v[210:213], v[4:7]
	v_mfma_f32_16x16x32_bf16 v[0:3], v[178:181], v[210:213], v[0:3]
	s_setprio 0
	s_barrier
	s_add_i32 s56, s56, 2
	s_add_u32 s22, s22, 0x100
	s_addc_u32 s23, s23, 0
	s_add_u32 s54, s54, 0x100
	s_addc_u32 s55, s55, 0
	s_cmpk_gt_u32 s56, 0x55
	s_cbranch_scc0 .LBB0_853
	s_and_b64 vcc, exec, s[10:11]
	s_cbranch_vccz .LBB0_856
	s_barrier
